# merge GEMM epilogues: all gate loads of an m-block in flight (16/8) instead of dependent pairs; out-GEMM half-tile epilogue batched
# speedup vs baseline: 1.0930x; 1.0279x over previous
; #define MFMA16(a, b, c) __builtin_amdgcn_mfma_f32_16x16x32_bf16((a), (b), (c), 0, 0, 0)
; DI float bf2f(bfr b) { return __uint_as_float(((unsigned)b) << 16); }
;     ...
;     __builtin_amdgcn_s_setprio(1);
; #pragma unroll
;     for (int ks = 0; ks < 2; ++ks)
; #pragma unroll
;       for (int m = 0; m < 4; ++m)
; #pragma unroll
;         for (int n = 0; n < NF; ++n) acc[m][n] = MFMA16(af[ks][m], bfg[ks][n], acc[m][n]);
;     __builtin_amdgcn_s_setprio(0);
; template <int NF>
; DI void merge_tile(const Params& p, int layer, int brow, int bcol, bool& first, bool hasNext, int nbrow, int nbcol) {
;     ...
; #pragma unroll
;     for (int m = 0; m < 4; ++m) {
;       const int row0 = brow + wr * 64 + m * 16 + fq * 4;
;       if (row0 < ROWS) {
; #pragma unroll
;         for (int n = 0; n < NF; ++n) {
;           const int col = bcol + wc * (NF * 16) + n * 16 + fr;
;           const bfr* gp = gmb + (long)row0 * 3072 + br * 1024 + col;
;           const float g0 = bf2f(gp[0]), g1 = bf2f(gp[3072]), g2 = bf2f(gp[2 * 3072]), g3 = bf2f(gp[3 * 3072]);
;           const unsigned t0 = tot[m][n][0], t1 = tot[m][n][1];
;           tot[m][n][0] = pack2(__uint_as_float(t0 << 16) + g0 * acc[m][n][0], __uint_as_float(t0 & 0xFFFF0000u) + g1 * acc[m][n][1]);
;           tot[m][n][1] = pack2(__uint_as_float(t1 << 16) + g2 * acc[m][n][2], __uint_as_float(t1 & 0xFFFF0000u) + g3 * acc[m][n][3]);
;         }
;       }
;     }
.LBB0_4966:
	ds_read_b128 v[74:77], v111
	ds_read_b128 v[118:121], v111 offset:2048
	ds_read_b128 v[122:125], v111 offset:4096
	ds_read_b128 v[132:135], v111 offset:6144
	ds_read_b128 v[136:139], v113
	ds_read_b128 v[140:143], v113 offset:2048
	ds_read_b128 v[144:147], v113 offset:4096
	ds_read_b128 v[148:151], v113 offset:6144
	ds_read_b128 v[152:155], v115
	ds_read_b128 v[180:183], v115 offset:2048
	ds_read_b128 v[184:187], v115 offset:4096
	ds_read_b128 v[188:191], v115 offset:6144
	ds_read_b128 v[192:195], v117
	ds_read_b128 v[196:199], v117 offset:2048
	ds_read_b128 v[200:203], v117 offset:4096
	ds_read_b128 v[204:207], v117 offset:6144
	s_waitcnt lgkmcnt(8)
	s_setprio 1
	v_mfma_f32_16x16x32_bf16 v[0:3], v[74:77], v[136:139], v[0:3]
	v_mfma_f32_16x16x32_bf16 v[4:7], v[74:77], v[140:143], v[4:7]
	v_mfma_f32_16x16x32_bf16 v[8:11], v[74:77], v[144:147], v[8:11]
	v_mfma_f32_16x16x32_bf16 v[12:15], v[74:77], v[148:151], v[12:15]
	v_mfma_f32_16x16x32_bf16 v[16:19], v[118:121], v[136:139], v[16:19]
	v_mfma_f32_16x16x32_bf16 v[20:23], v[118:121], v[140:143], v[20:23]
	v_mfma_f32_16x16x32_bf16 v[24:27], v[118:121], v[144:147], v[24:27]
	v_mfma_f32_16x16x32_bf16 v[28:31], v[118:121], v[148:151], v[28:31]
	v_mfma_f32_16x16x32_bf16 v[74:77], v[122:125], v[136:139], v[32:35]
	v_mfma_f32_16x16x32_bf16 v[110:113], v[122:125], v[140:143], v[36:39]
	v_mfma_f32_16x16x32_bf16 v[114:117], v[122:125], v[144:147], v[40:43]
	v_mfma_f32_16x16x32_bf16 v[118:121], v[122:125], v[148:151], v[44:47]
	v_mfma_f32_16x16x32_bf16 v[122:125], v[132:135], v[136:139], v[48:51]
	v_mfma_f32_16x16x32_bf16 v[136:139], v[132:135], v[140:143], v[52:55]
	v_mfma_f32_16x16x32_bf16 v[140:143], v[132:135], v[144:147], v[56:59]
	v_mfma_f32_16x16x32_bf16 v[132:135], v[132:135], v[148:151], v[60:63]
	s_waitcnt lgkmcnt(0)
	v_mfma_f32_16x16x32_bf16 v[60:63], v[152:155], v[192:195], v[0:3]
	v_mfma_f32_16x16x32_bf16 v[56:59], v[152:155], v[196:199], v[4:7]
	v_mfma_f32_16x16x32_bf16 v[52:55], v[152:155], v[200:203], v[8:11]
	v_mfma_f32_16x16x32_bf16 v[48:51], v[152:155], v[204:207], v[12:15]
	v_mfma_f32_16x16x32_bf16 v[44:47], v[180:183], v[192:195], v[16:19]
	v_mfma_f32_16x16x32_bf16 v[40:43], v[180:183], v[196:199], v[20:23]
	v_mfma_f32_16x16x32_bf16 v[36:39], v[180:183], v[200:203], v[24:27]
	v_mfma_f32_16x16x32_bf16 v[32:35], v[180:183], v[204:207], v[28:31]
	v_mfma_f32_16x16x32_bf16 v[28:31], v[184:187], v[192:195], v[74:77]
	v_mfma_f32_16x16x32_bf16 v[24:27], v[184:187], v[196:199], v[110:113]
	v_mfma_f32_16x16x32_bf16 v[20:23], v[184:187], v[200:203], v[114:117]
	v_mfma_f32_16x16x32_bf16 v[16:19], v[184:187], v[204:207], v[118:121]
	v_mfma_f32_16x16x32_bf16 v[12:15], v[188:191], v[192:195], v[122:125]
	v_mfma_f32_16x16x32_bf16 v[8:11], v[188:191], v[196:199], v[136:139]
	v_mfma_f32_16x16x32_bf16 v[4:7], v[188:191], v[200:203], v[140:143]
	v_mfma_f32_16x16x32_bf16 v[0:3], v[188:191], v[204:207], v[132:135]
	s_setprio 0
	s_and_saveexec_b64 s[20:21], s[6:7]
	s_cbranch_execz .LBB0_4968
	v_lshl_add_u64 v[110:111], v[66:67], 0, s[18:19]
	v_add_co_u32_e32 v112, vcc, 0xfe9c000, v110
	s_nop 1
	v_addc_co_u32_e32 v113, vcc, 0, v111, vcc
	v_add_co_u32_e32 v114, vcc, 0xfe9e000, v110
	s_nop 1
	v_addc_co_u32_e32 v115, vcc, 0, v111, vcc
	v_add_co_u32_e32 v116, vcc, s88, v110
	s_nop 1
	v_addc_co_u32_e32 v117, vcc, 0, v111, vcc
	v_add_co_u32_e32 v118, vcc, s93, v110
	s_nop 1
	v_addc_co_u32_e32 v119, vcc, 0, v111, vcc
	global_load_ushort v132, v[112:113], off offset:3072
	global_load_ushort v133, v[114:115], off offset:1024
	global_load_ushort v134, v[116:117], off offset:3072
	global_load_ushort v135, v[118:119], off offset:1024
	global_load_ushort v136, v[112:113], off offset:3104
	global_load_ushort v137, v[114:115], off offset:1056
	global_load_ushort v138, v[116:117], off offset:3104
	global_load_ushort v139, v[118:119], off offset:1056
	global_load_ushort v140, v[112:113], off offset:3136
	global_load_ushort v141, v[114:115], off offset:1088
	global_load_ushort v142, v[116:117], off offset:3136
	global_load_ushort v143, v[118:119], off offset:1088
	global_load_ushort v144, v[112:113], off offset:3168
	global_load_ushort v145, v[114:115], off offset:1120
	global_load_ushort v146, v[116:117], off offset:3168
	global_load_ushort v147, v[118:119], off offset:1120
	s_waitcnt vmcnt(0)
	v_lshlrev_b32_e32 v120, 16, v101
	v_and_b32_e32 v121, 0xffff0000, v101
	v_lshlrev_b32_e32 v132, 16, v132
	v_lshlrev_b32_e32 v133, 16, v133
	v_pk_fma_f32 v[122:123], v[60:61], v[132:133], v[120:121]
	s_nop 0
	v_cvt_pk_bf16_f32 v101, v122, v123
	v_lshlrev_b32_e32 v120, 16, v102
	v_and_b32_e32 v121, 0xffff0000, v102
	v_lshlrev_b32_e32 v134, 16, v134
	v_lshlrev_b32_e32 v135, 16, v135
	v_pk_fma_f32 v[122:123], v[62:63], v[134:135], v[120:121]
	s_nop 0
	v_cvt_pk_bf16_f32 v102, v122, v123
	v_lshlrev_b32_e32 v120, 16, v103
	v_and_b32_e32 v121, 0xffff0000, v103
	v_lshlrev_b32_e32 v136, 16, v136
	v_lshlrev_b32_e32 v137, 16, v137
	v_pk_fma_f32 v[122:123], v[56:57], v[136:137], v[120:121]
	s_nop 0
	v_cvt_pk_bf16_f32 v103, v122, v123
	v_lshlrev_b32_e32 v120, 16, v96
	v_and_b32_e32 v121, 0xffff0000, v96
	v_lshlrev_b32_e32 v138, 16, v138
	v_lshlrev_b32_e32 v139, 16, v139
	v_pk_fma_f32 v[122:123], v[58:59], v[138:139], v[120:121]
	s_nop 0
	v_cvt_pk_bf16_f32 v96, v122, v123
	v_lshlrev_b32_e32 v120, 16, v105
	v_and_b32_e32 v121, 0xffff0000, v105
	v_lshlrev_b32_e32 v140, 16, v140
	v_lshlrev_b32_e32 v141, 16, v141
	v_pk_fma_f32 v[122:123], v[52:53], v[140:141], v[120:121]
	s_nop 0
	v_cvt_pk_bf16_f32 v105, v122, v123
	v_lshlrev_b32_e32 v120, 16, v95
	v_and_b32_e32 v121, 0xffff0000, v95
	v_lshlrev_b32_e32 v142, 16, v142
	v_lshlrev_b32_e32 v143, 16, v143
	v_pk_fma_f32 v[122:123], v[54:55], v[142:143], v[120:121]
	s_nop 0
	v_cvt_pk_bf16_f32 v95, v122, v123
	v_lshlrev_b32_e32 v120, 16, v104
	v_and_b32_e32 v121, 0xffff0000, v104
	v_lshlrev_b32_e32 v144, 16, v144
	v_lshlrev_b32_e32 v145, 16, v145
	v_pk_fma_f32 v[122:123], v[48:49], v[144:145], v[120:121]
	s_nop 0
	v_cvt_pk_bf16_f32 v104, v122, v123
	v_lshlrev_b32_e32 v120, 16, v109
	v_and_b32_e32 v121, 0xffff0000, v109
	v_lshlrev_b32_e32 v146, 16, v146
	v_lshlrev_b32_e32 v147, 16, v147
	v_pk_fma_f32 v[122:123], v[50:51], v[146:147], v[120:121]
	s_nop 0
	v_cvt_pk_bf16_f32 v109, v122, v123
; DI float bf2f(bfr b) { return __uint_as_float(((unsigned)b) << 16); }
; template <int NF>
; DI void merge_tile(const Params& p, int layer, int brow, int bcol, bool& first, bool hasNext, int nbrow, int nbcol) {
;     ...
; #pragma unroll
;     for (int m = 0; m < 4; ++m) {
;       const int row0 = brow + wr * 64 + m * 16 + fq * 4;
;       if (row0 < ROWS) {
; #pragma unroll
;         for (int n = 0; n < NF; ++n) {
;           const int col = bcol + wc * (NF * 16) + n * 16 + fr;
;           const bfr* gp = gmb + (long)row0 * 3072 + br * 1024 + col;
;           const float g0 = bf2f(gp[0]), g1 = bf2f(gp[3072]), g2 = bf2f(gp[2 * 3072]), g3 = bf2f(gp[3 * 3072]);
;           const unsigned t0 = tot[m][n][0], t1 = tot[m][n][1];
;           tot[m][n][0] = pack2(__uint_as_float(t0 << 16) + g0 * acc[m][n][0], __uint_as_float(t0 & 0xFFFF0000u) + g1 * acc[m][n][1]);
;           tot[m][n][1] = pack2(__uint_as_float(t1 << 16) + g2 * acc[m][n][2], __uint_as_float(t1 & 0xFFFF0000u) + g3 * acc[m][n][3]);
;         }
;       }
;     }
.LBB0_4968:
	s_or_b64 exec, exec, s[20:21]
	s_and_saveexec_b64 s[20:21], s[4:5]
	s_mov_b64 s[52:53], 0x6cc8480
	s_mov_b64 s[54:55], 0x6cd8480
	s_mov_b64 s[56:57], 0x6ce8480
	s_cbranch_execz .LBB0_4971
	v_lshl_add_u64 v[110:111], v[68:69], 0, s[18:19]
	v_add_co_u32_e32 v112, vcc, 0xfe9c000, v110
	s_nop 1
	v_addc_co_u32_e32 v113, vcc, 0, v111, vcc
	v_add_co_u32_e32 v114, vcc, 0xfe9e000, v110
	s_nop 1
	v_addc_co_u32_e32 v115, vcc, 0, v111, vcc
	v_add_co_u32_e32 v116, vcc, s88, v110
	s_nop 1
	v_addc_co_u32_e32 v117, vcc, 0, v111, vcc
	v_add_co_u32_e32 v118, vcc, s93, v110
	s_nop 1
	v_addc_co_u32_e32 v119, vcc, 0, v111, vcc
	global_load_ushort v132, v[112:113], off offset:3072
	global_load_ushort v133, v[114:115], off offset:1024
	global_load_ushort v134, v[116:117], off offset:3072
	global_load_ushort v135, v[118:119], off offset:1024
	global_load_ushort v136, v[112:113], off offset:3104
	global_load_ushort v137, v[114:115], off offset:1056
	global_load_ushort v138, v[116:117], off offset:3104
	global_load_ushort v139, v[118:119], off offset:1056
	global_load_ushort v140, v[112:113], off offset:3136
	global_load_ushort v141, v[114:115], off offset:1088
	global_load_ushort v142, v[116:117], off offset:3136
	global_load_ushort v143, v[118:119], off offset:1088
	global_load_ushort v144, v[112:113], off offset:3168
	global_load_ushort v145, v[114:115], off offset:1120
	global_load_ushort v146, v[116:117], off offset:3168
	global_load_ushort v147, v[118:119], off offset:1120
	s_waitcnt vmcnt(0)
	v_lshlrev_b32_e32 v120, 16, v94
	v_and_b32_e32 v121, 0xffff0000, v94
	v_lshlrev_b32_e32 v132, 16, v132
	v_lshlrev_b32_e32 v133, 16, v133
	v_pk_fma_f32 v[122:123], v[44:45], v[132:133], v[120:121]
	s_nop 0
	v_cvt_pk_bf16_f32 v94, v122, v123
	v_lshlrev_b32_e32 v120, 16, v97
	v_and_b32_e32 v121, 0xffff0000, v97
	v_lshlrev_b32_e32 v134, 16, v134
	v_lshlrev_b32_e32 v135, 16, v135
	v_pk_fma_f32 v[122:123], v[46:47], v[134:135], v[120:121]
	s_nop 0
	v_cvt_pk_bf16_f32 v97, v122, v123
	v_lshlrev_b32_e32 v120, 16, v98
	v_and_b32_e32 v121, 0xffff0000, v98
	v_lshlrev_b32_e32 v136, 16, v136
	v_lshlrev_b32_e32 v137, 16, v137
	v_pk_fma_f32 v[122:123], v[40:41], v[136:137], v[120:121]
	s_nop 0
	v_cvt_pk_bf16_f32 v98, v122, v123
	v_lshlrev_b32_e32 v120, 16, v89
	v_and_b32_e32 v121, 0xffff0000, v89
	v_lshlrev_b32_e32 v138, 16, v138
	v_lshlrev_b32_e32 v139, 16, v139
	v_pk_fma_f32 v[122:123], v[42:43], v[138:139], v[120:121]
	s_nop 0
	v_cvt_pk_bf16_f32 v89, v122, v123
	v_lshlrev_b32_e32 v120, 16, v100
	v_and_b32_e32 v121, 0xffff0000, v100
	v_lshlrev_b32_e32 v140, 16, v140
	v_lshlrev_b32_e32 v141, 16, v141
	v_pk_fma_f32 v[122:123], v[36:37], v[140:141], v[120:121]
	s_nop 0
	v_cvt_pk_bf16_f32 v100, v122, v123
	v_lshlrev_b32_e32 v120, 16, v88
	v_and_b32_e32 v121, 0xffff0000, v88
	v_lshlrev_b32_e32 v142, 16, v142
	v_lshlrev_b32_e32 v143, 16, v143
	v_pk_fma_f32 v[122:123], v[38:39], v[142:143], v[120:121]
	s_nop 0
	v_cvt_pk_bf16_f32 v88, v122, v123
	v_lshlrev_b32_e32 v120, 16, v99
	v_and_b32_e32 v121, 0xffff0000, v99
	v_lshlrev_b32_e32 v144, 16, v144
	v_lshlrev_b32_e32 v145, 16, v145
	v_pk_fma_f32 v[122:123], v[32:33], v[144:145], v[120:121]
	s_nop 0
	v_cvt_pk_bf16_f32 v99, v122, v123
	v_lshlrev_b32_e32 v120, 16, v108
	v_and_b32_e32 v121, 0xffff0000, v108
	v_lshlrev_b32_e32 v146, 16, v146
	v_lshlrev_b32_e32 v147, 16, v147
	v_pk_fma_f32 v[122:123], v[34:35], v[146:147], v[120:121]
	s_nop 0
	v_cvt_pk_bf16_f32 v108, v122, v123
	s_or_b64 exec, exec, s[20:21]
	s_and_saveexec_b64 s[20:21], s[2:3]
	s_cbranch_execnz .LBB0_4972

; DI float bf2f(bfr b) { return __uint_as_float(((unsigned)b) << 16); }
; template <int NF>
; DI void merge_tile(const Params& p, int layer, int brow, int bcol, bool& first, bool hasNext, int nbrow, int nbcol) {
;     ...
; #pragma unroll
;     for (int m = 0; m < 4; ++m) {
;       const int row0 = brow + wr * 64 + m * 16 + fq * 4;
;       if (row0 < ROWS) {
; #pragma unroll
;         for (int n = 0; n < NF; ++n) {
;           const int col = bcol + wc * (NF * 16) + n * 16 + fr;
;           const bfr* gp = gmb + (long)row0 * 3072 + br * 1024 + col;
;           const float g0 = bf2f(gp[0]), g1 = bf2f(gp[3072]), g2 = bf2f(gp[2 * 3072]), g3 = bf2f(gp[3 * 3072]);
;           const unsigned t0 = tot[m][n][0], t1 = tot[m][n][1];
;           tot[m][n][0] = pack2(__uint_as_float(t0 << 16) + g0 * acc[m][n][0], __uint_as_float(t0 & 0xFFFF0000u) + g1 * acc[m][n][1]);
;           tot[m][n][1] = pack2(__uint_as_float(t1 << 16) + g2 * acc[m][n][2], __uint_as_float(t1 & 0xFFFF0000u) + g3 * acc[m][n][3]);
;         }
;       }
;     }
.LBB0_4972:
	v_lshl_add_u64 v[110:111], v[70:71], 0, s[18:19]
	v_add_co_u32_e32 v112, vcc, 0xfe9c000, v110
	s_nop 1
	v_addc_co_u32_e32 v113, vcc, 0, v111, vcc
	v_add_co_u32_e32 v114, vcc, 0xfe9e000, v110
	s_nop 1
	v_addc_co_u32_e32 v115, vcc, 0, v111, vcc
	v_add_co_u32_e32 v116, vcc, s88, v110
	s_nop 1
	v_addc_co_u32_e32 v117, vcc, 0, v111, vcc
	v_add_co_u32_e32 v118, vcc, s93, v110
	s_nop 1
	v_addc_co_u32_e32 v119, vcc, 0, v111, vcc
	global_load_ushort v132, v[112:113], off offset:3072
	global_load_ushort v133, v[114:115], off offset:1024
	global_load_ushort v134, v[116:117], off offset:3072
	global_load_ushort v135, v[118:119], off offset:1024
	global_load_ushort v136, v[112:113], off offset:3104
	global_load_ushort v137, v[114:115], off offset:1056
	global_load_ushort v138, v[116:117], off offset:3104
	global_load_ushort v139, v[118:119], off offset:1056
	global_load_ushort v140, v[112:113], off offset:3136
	global_load_ushort v141, v[114:115], off offset:1088
	global_load_ushort v142, v[116:117], off offset:3136
	global_load_ushort v143, v[118:119], off offset:1088
	global_load_ushort v144, v[112:113], off offset:3168
	global_load_ushort v145, v[114:115], off offset:1120
	global_load_ushort v146, v[116:117], off offset:3168
	global_load_ushort v147, v[118:119], off offset:1120
	s_waitcnt vmcnt(0)
	v_lshlrev_b32_e32 v120, 16, v87
	v_and_b32_e32 v121, 0xffff0000, v87
	v_lshlrev_b32_e32 v132, 16, v132
	v_lshlrev_b32_e32 v133, 16, v133
	v_pk_fma_f32 v[122:123], v[28:29], v[132:133], v[120:121]
	s_nop 0
	v_cvt_pk_bf16_f32 v87, v122, v123
	v_lshlrev_b32_e32 v120, 16, v90
	v_and_b32_e32 v121, 0xffff0000, v90
	v_lshlrev_b32_e32 v134, 16, v134
	v_lshlrev_b32_e32 v135, 16, v135
	v_pk_fma_f32 v[122:123], v[30:31], v[134:135], v[120:121]
	s_nop 0
	v_cvt_pk_bf16_f32 v90, v122, v123
	v_lshlrev_b32_e32 v120, 16, v91
	v_and_b32_e32 v121, 0xffff0000, v91
	v_lshlrev_b32_e32 v136, 16, v136
	v_lshlrev_b32_e32 v137, 16, v137
	v_pk_fma_f32 v[122:123], v[24:25], v[136:137], v[120:121]
	s_nop 0
	v_cvt_pk_bf16_f32 v91, v122, v123
	v_lshlrev_b32_e32 v120, 16, v82
	v_and_b32_e32 v121, 0xffff0000, v82
	v_lshlrev_b32_e32 v138, 16, v138
	v_lshlrev_b32_e32 v139, 16, v139
	v_pk_fma_f32 v[122:123], v[26:27], v[138:139], v[120:121]
	s_nop 0
	v_cvt_pk_bf16_f32 v82, v122, v123
	v_lshlrev_b32_e32 v120, 16, v93
	v_and_b32_e32 v121, 0xffff0000, v93
	v_lshlrev_b32_e32 v140, 16, v140
	v_lshlrev_b32_e32 v141, 16, v141
	v_pk_fma_f32 v[122:123], v[20:21], v[140:141], v[120:121]
	s_nop 0
	v_cvt_pk_bf16_f32 v93, v122, v123
	v_lshlrev_b32_e32 v120, 16, v81
	v_and_b32_e32 v121, 0xffff0000, v81
	v_lshlrev_b32_e32 v142, 16, v142
	v_lshlrev_b32_e32 v143, 16, v143
	v_pk_fma_f32 v[122:123], v[22:23], v[142:143], v[120:121]
	s_nop 0
	v_cvt_pk_bf16_f32 v81, v122, v123
	v_lshlrev_b32_e32 v120, 16, v92
	v_and_b32_e32 v121, 0xffff0000, v92
	v_lshlrev_b32_e32 v144, 16, v144
	v_lshlrev_b32_e32 v145, 16, v145
	v_pk_fma_f32 v[122:123], v[16:17], v[144:145], v[120:121]
	s_nop 0
	v_cvt_pk_bf16_f32 v92, v122, v123
	v_lshlrev_b32_e32 v120, 16, v107
	v_and_b32_e32 v121, 0xffff0000, v107
	v_lshlrev_b32_e32 v146, 16, v146
	v_lshlrev_b32_e32 v147, 16, v147
	v_pk_fma_f32 v[122:123], v[18:19], v[146:147], v[120:121]
	s_nop 0
	v_cvt_pk_bf16_f32 v107, v122, v123
	s_or_b64 exec, exec, s[20:21]
	s_and_saveexec_b64 s[20:21], s[0:1]
	s_cbranch_execz .LBB0_4959
.LBB0_4973:
	v_lshl_add_u64 v[110:111], v[72:73], 0, s[18:19]
	v_add_co_u32_e32 v112, vcc, 0xfe9c000, v110
	s_nop 1
	v_addc_co_u32_e32 v113, vcc, 0, v111, vcc
	v_add_co_u32_e32 v114, vcc, 0xfe9e000, v110
	s_nop 1
	v_addc_co_u32_e32 v115, vcc, 0, v111, vcc
	v_add_co_u32_e32 v116, vcc, s88, v110
	s_nop 1
	v_addc_co_u32_e32 v117, vcc, 0, v111, vcc
	v_add_co_u32_e32 v118, vcc, s93, v110
	s_nop 1
	v_addc_co_u32_e32 v119, vcc, 0, v111, vcc
	global_load_ushort v132, v[112:113], off offset:3072
	global_load_ushort v133, v[114:115], off offset:1024
	global_load_ushort v134, v[116:117], off offset:3072
	global_load_ushort v135, v[118:119], off offset:1024
	global_load_ushort v136, v[112:113], off offset:3104
	global_load_ushort v137, v[114:115], off offset:1056
	global_load_ushort v138, v[116:117], off offset:3104
	global_load_ushort v139, v[118:119], off offset:1056
	global_load_ushort v140, v[112:113], off offset:3136
	global_load_ushort v141, v[114:115], off offset:1088
	global_load_ushort v142, v[116:117], off offset:3136
	global_load_ushort v143, v[118:119], off offset:1088
	global_load_ushort v144, v[112:113], off offset:3168
	global_load_ushort v145, v[114:115], off offset:1120
	global_load_ushort v146, v[116:117], off offset:3168
	global_load_ushort v147, v[118:119], off offset:1120
	s_waitcnt vmcnt(0)
	v_lshlrev_b32_e32 v120, 16, v80
	v_and_b32_e32 v121, 0xffff0000, v80
	v_lshlrev_b32_e32 v132, 16, v132
	v_lshlrev_b32_e32 v133, 16, v133
	v_pk_fma_f32 v[122:123], v[12:13], v[132:133], v[120:121]
	s_nop 0
	v_cvt_pk_bf16_f32 v80, v122, v123
	v_lshlrev_b32_e32 v120, 16, v83
	v_and_b32_e32 v121, 0xffff0000, v83
	v_lshlrev_b32_e32 v134, 16, v134
	v_lshlrev_b32_e32 v135, 16, v135
	v_pk_fma_f32 v[122:123], v[14:15], v[134:135], v[120:121]
	s_nop 0
	v_cvt_pk_bf16_f32 v83, v122, v123
	v_lshlrev_b32_e32 v120, 16, v84
	v_and_b32_e32 v121, 0xffff0000, v84
	v_lshlrev_b32_e32 v136, 16, v136
	v_lshlrev_b32_e32 v137, 16, v137
	v_pk_fma_f32 v[122:123], v[8:9], v[136:137], v[120:121]
	s_nop 0
	v_cvt_pk_bf16_f32 v84, v122, v123
	v_lshlrev_b32_e32 v120, 16, v79
	v_and_b32_e32 v121, 0xffff0000, v79
	v_lshlrev_b32_e32 v138, 16, v138
	v_lshlrev_b32_e32 v139, 16, v139
	v_pk_fma_f32 v[122:123], v[10:11], v[138:139], v[120:121]
	s_nop 0
	v_cvt_pk_bf16_f32 v79, v122, v123
	v_lshlrev_b32_e32 v120, 16, v86
	v_and_b32_e32 v121, 0xffff0000, v86
	v_lshlrev_b32_e32 v140, 16, v140
	v_lshlrev_b32_e32 v141, 16, v141
	v_pk_fma_f32 v[122:123], v[4:5], v[140:141], v[120:121]
	s_nop 0
	v_cvt_pk_bf16_f32 v86, v122, v123
	v_lshlrev_b32_e32 v120, 16, v78
	v_and_b32_e32 v121, 0xffff0000, v78
	v_lshlrev_b32_e32 v142, 16, v142
	v_lshlrev_b32_e32 v143, 16, v143
	v_pk_fma_f32 v[122:123], v[6:7], v[142:143], v[120:121]
	s_nop 0
	v_cvt_pk_bf16_f32 v78, v122, v123
	v_lshlrev_b32_e32 v120, 16, v85
	v_and_b32_e32 v121, 0xffff0000, v85
	v_lshlrev_b32_e32 v144, 16, v144
	v_lshlrev_b32_e32 v145, 16, v145
	v_pk_fma_f32 v[122:123], v[0:1], v[144:145], v[120:121]
	s_nop 0
	v_cvt_pk_bf16_f32 v85, v122, v123
	v_lshlrev_b32_e32 v120, 16, v106
	v_and_b32_e32 v121, 0xffff0000, v106
	v_lshlrev_b32_e32 v146, 16, v146
	v_lshlrev_b32_e32 v147, 16, v147
	v_pk_fma_f32 v[122:123], v[2:3], v[146:147], v[120:121]
	s_nop 0
	v_cvt_pk_bf16_f32 v106, v122, v123
	s_branch .LBB0_4959

;     ...
;     const unsigned bo = (kt & 1) * 32768;
;     bf16x8 af[2][4], bfg[2][4];
;     if (NF == 4) {
;       asm volatile(
;           "ds_read_b128 %0, %16\n\tds_read_b128 %1, %16 offset:2048\n\tds_read_b128 %2, %16 offset:4096\n\tds_read_b128 %3, %16 offset:6144\n\t"
;           "ds_read_b128 %4, %17\n\tds_read_b128 %5, %17 offset:2048\n\tds_read_b128 %6, %17 offset:4096\n\tds_read_b128 %7, %17 offset:6144\n\t"
;           "ds_read_b128 %8, %18\n\tds_read_b128 %9, %18 offset:2048\n\tds_read_b128 %10, %18 offset:4096\n\tds_read_b128 %11, %18 offset:6144\n\t"
;           "ds_read_b128 %12, %19\n\tds_read_b128 %13, %19 offset:2048\n\tds_read_b128 %14, %19 offset:4096\n\tds_read_b128 %15, %19 offset:6144\n\t"
;           "s_waitcnt lgkmcnt(0)"
;           : "=&v"(af[0][0]), "=&v"(af[0][1]), "=&v"(af[0][2]), "=&v"(af[0][3]), "=&v"(bfg[0][0]), "=&v"(bfg[0][1]), "=&v"(bfg[0][2]), "=&v"(bfg[0][3]),
;             "=&v"(af[1][0]), "=&v"(af[1][1]), "=&v"(af[1][2]), "=&v"(af[1][3]), "=&v"(bfg[1][0]), "=&v"(bfg[1][1]), "=&v"(bfg[1][2]), "=&v"(bfg[1][3])
;           : "v"(arow + sw0 + bo), "v"(brw + sw0 + bo), "v"(arow + sw1 + bo), "v"(brw + sw1 + bo)
;           : "memory");
;     } else {
;       asm volatile(
;           "ds_read_b128 %0, %12\n\tds_read_b128 %1, %12 offset:2048\n\tds_read_b128 %2, %12 offset:4096\n\tds_read_b128 %3, %12 offset:6144\n\t"
;           "ds_read_b128 %4, %13\n\tds_read_b128 %5, %13 offset:2048\n\t"
;           "ds_read_b128 %6, %14\n\tds_read_b128 %7, %14 offset:2048\n\tds_read_b128 %8, %14 offset:4096\n\tds_read_b128 %9, %14 offset:6144\n\t"
;           "ds_read_b128 %10, %15\n\tds_read_b128 %11, %15 offset:2048\n\t"
;           "s_waitcnt lgkmcnt(0)"
;           : "=&v"(af[0][0]), "=&v"(af[0][1]), "=&v"(af[0][2]), "=&v"(af[0][3]), "=&v"(bfg[0][0]), "=&v"(bfg[0][1]),
;             "=&v"(af[1][0]), "=&v"(af[1][1]), "=&v"(af[1][2]), "=&v"(af[1][3]), "=&v"(bfg[1][0]), "=&v"(bfg[1][1])
;           : "v"(arow + sw0 + bo), "v"(brw + sw0 + bo), "v"(arow + sw1 + bo), "v"(brw + sw1 + bo)
;           : "memory");
;     }
;     __builtin_amdgcn_s_setprio(1);
; #pragma unroll
;     for (int ks = 0; ks < 2; ++ks)
; #pragma unroll
;       for (int m = 0; m < 4; ++m)
; #pragma unroll
;         for (int n = 0; n < NF; ++n) acc[m][n] = MFMA16(af[ks][m], bfg[ks][n], acc[m][n]);
;     __builtin_amdgcn_s_setprio(0);
;   }
.LBB0_4991:
	ds_read_b128 v[58:61], v63
	ds_read_b128 v[68:71], v63 offset:2048
	ds_read_b128 v[72:75], v63 offset:4096
	ds_read_b128 v[76:79], v63 offset:6144
	ds_read_b128 v[80:83], v64
	ds_read_b128 v[84:87], v64 offset:2048
	ds_read_b128 v[88:91], v65
	ds_read_b128 v[92:95], v65 offset:2048
	ds_read_b128 v[96:99], v65 offset:4096
	ds_read_b128 v[100:103], v65 offset:6144
	ds_read_b128 v[104:107], v67
	ds_read_b128 v[108:111], v67 offset:2048
	s_waitcnt lgkmcnt(0)
	s_setprio 1
	v_mfma_f32_16x16x32_bf16 v[0:3], v[58:61], v[80:83], v[0:3]
	v_mfma_f32_16x16x32_bf16 v[4:7], v[58:61], v[84:87], v[4:7]
	v_mfma_f32_16x16x32_bf16 v[8:11], v[68:71], v[80:83], v[8:11]
	v_mfma_f32_16x16x32_bf16 v[12:15], v[68:71], v[84:87], v[12:15]
	v_mfma_f32_16x16x32_bf16 v[58:61], v[72:75], v[80:83], v[16:19]
	v_mfma_f32_16x16x32_bf16 v[62:65], v[72:75], v[84:87], v[20:23]
	v_mfma_f32_16x16x32_bf16 v[66:69], v[76:79], v[80:83], v[24:27]
	v_mfma_f32_16x16x32_bf16 v[70:73], v[76:79], v[84:87], v[28:31]
	v_mfma_f32_16x16x32_bf16 v[28:31], v[88:91], v[104:107], v[0:3]
	v_mfma_f32_16x16x32_bf16 v[24:27], v[88:91], v[108:111], v[4:7]
	v_mfma_f32_16x16x32_bf16 v[20:23], v[92:95], v[104:107], v[8:11]
	v_mfma_f32_16x16x32_bf16 v[16:19], v[92:95], v[108:111], v[12:15]
	v_mfma_f32_16x16x32_bf16 v[12:15], v[96:99], v[104:107], v[58:61]
	v_mfma_f32_16x16x32_bf16 v[8:11], v[96:99], v[108:111], v[62:65]
	v_mfma_f32_16x16x32_bf16 v[4:7], v[100:103], v[104:107], v[66:69]
	v_mfma_f32_16x16x32_bf16 v[0:3], v[100:103], v[108:111], v[70:73]
	s_setprio 0
	s_and_saveexec_b64 s[16:17], s[6:7]
	s_cbranch_execz .LBB0_4995
	v_lshl_add_u64 v[110:111], v[34:35], 0, s[14:15]
	v_add_co_u32_e32 v112, vcc, 0xfe9c000, v110
	s_nop 1
	v_addc_co_u32_e32 v113, vcc, 0, v111, vcc
	v_add_co_u32_e32 v114, vcc, 0xfe9e000, v110
	s_nop 1
	v_addc_co_u32_e32 v115, vcc, 0, v111, vcc
	v_add_co_u32_e32 v116, vcc, s88, v110
	s_nop 1
	v_addc_co_u32_e32 v117, vcc, 0, v111, vcc
	v_add_co_u32_e32 v118, vcc, s93, v110
	s_nop 1
	v_addc_co_u32_e32 v119, vcc, 0, v111, vcc
	global_load_ushort v132, v[112:113], off offset:3072
	global_load_ushort v133, v[114:115], off offset:1024
	global_load_ushort v134, v[116:117], off offset:3072
	global_load_ushort v135, v[118:119], off offset:1024
	global_load_ushort v136, v[112:113], off offset:3104
	global_load_ushort v137, v[114:115], off offset:1056
	global_load_ushort v138, v[116:117], off offset:3104
	global_load_ushort v139, v[118:119], off offset:1056
	s_waitcnt vmcnt(0)
	v_lshlrev_b32_e32 v120, 16, v52
	v_and_b32_e32 v121, 0xffff0000, v52
	v_lshlrev_b32_e32 v132, 16, v132
	v_lshlrev_b32_e32 v133, 16, v133
	v_pk_fma_f32 v[122:123], v[28:29], v[132:133], v[120:121]
	s_nop 0
	v_cvt_pk_bf16_f32 v52, v122, v123
	v_lshlrev_b32_e32 v120, 16, v53
	v_and_b32_e32 v121, 0xffff0000, v53
	v_lshlrev_b32_e32 v134, 16, v134
	v_lshlrev_b32_e32 v135, 16, v135
	v_pk_fma_f32 v[122:123], v[30:31], v[134:135], v[120:121]
	s_nop 0
	v_cvt_pk_bf16_f32 v53, v122, v123
	v_lshlrev_b32_e32 v120, 16, v49
	v_and_b32_e32 v121, 0xffff0000, v49
	v_lshlrev_b32_e32 v136, 16, v136
	v_lshlrev_b32_e32 v137, 16, v137
	v_pk_fma_f32 v[122:123], v[24:25], v[136:137], v[120:121]
	s_nop 0
	v_cvt_pk_bf16_f32 v49, v122, v123
	v_lshlrev_b32_e32 v120, 16, v57
	v_and_b32_e32 v121, 0xffff0000, v57
	v_lshlrev_b32_e32 v138, 16, v138
	v_lshlrev_b32_e32 v139, 16, v139
	v_pk_fma_f32 v[122:123], v[26:27], v[138:139], v[120:121]
	s_nop 0
	v_cvt_pk_bf16_f32 v57, v122, v123
	s_or_b64 exec, exec, s[16:17]
	s_and_saveexec_b64 s[16:17], s[4:5]
	s_cbranch_execnz .LBB0_4996

; DI float bf2f(bfr b) { return __uint_as_float(((unsigned)b) << 16); }
; template <int NF>
; DI void merge_tile(const Params& p, int layer, int brow, int bcol, bool& first, bool hasNext, int nbrow, int nbcol) {
;     ...
; #pragma unroll
;     for (int m = 0; m < 4; ++m) {
;       const int row0 = brow + wr * 64 + m * 16 + fq * 4;
;       if (row0 < ROWS) {
; #pragma unroll
;         for (int n = 0; n < NF; ++n) {
;           const int col = bcol + wc * (NF * 16) + n * 16 + fr;
;           const bfr* gp = gmb + (long)row0 * 3072 + br * 1024 + col;
;           const float g0 = bf2f(gp[0]), g1 = bf2f(gp[3072]), g2 = bf2f(gp[2 * 3072]), g3 = bf2f(gp[3 * 3072]);
;           const unsigned t0 = tot[m][n][0], t1 = tot[m][n][1];
;           tot[m][n][0] = pack2(__uint_as_float(t0 << 16) + g0 * acc[m][n][0], __uint_as_float(t0 & 0xFFFF0000u) + g1 * acc[m][n][1]);
;           tot[m][n][1] = pack2(__uint_as_float(t1 << 16) + g2 * acc[m][n][2], __uint_as_float(t1 & 0xFFFF0000u) + g3 * acc[m][n][3]);
;         }
;       }
;     }
.LBB0_4994:
	v_lshl_add_u64 v[110:111], v[38:39], 0, s[14:15]
	v_add_co_u32_e32 v112, vcc, 0xfe9c000, v110
	s_nop 1
	v_addc_co_u32_e32 v113, vcc, 0, v111, vcc
	v_add_co_u32_e32 v114, vcc, 0xfe9e000, v110
	s_nop 1
	v_addc_co_u32_e32 v115, vcc, 0, v111, vcc
	v_add_co_u32_e32 v116, vcc, s88, v110
	s_nop 1
	v_addc_co_u32_e32 v117, vcc, 0, v111, vcc
	v_add_co_u32_e32 v118, vcc, s93, v110
	s_nop 1
	v_addc_co_u32_e32 v119, vcc, 0, v111, vcc
	global_load_ushort v132, v[112:113], off offset:3072
	global_load_ushort v133, v[114:115], off offset:1024
	global_load_ushort v134, v[116:117], off offset:3072
	global_load_ushort v135, v[118:119], off offset:1024
	global_load_ushort v136, v[112:113], off offset:3104
	global_load_ushort v137, v[114:115], off offset:1056
	global_load_ushort v138, v[116:117], off offset:3104
	global_load_ushort v139, v[118:119], off offset:1056
	s_waitcnt vmcnt(0)
	v_lshlrev_b32_e32 v120, 16, v47
	v_and_b32_e32 v121, 0xffff0000, v47
	v_lshlrev_b32_e32 v132, 16, v132
	v_lshlrev_b32_e32 v133, 16, v133
	v_pk_fma_f32 v[122:123], v[12:13], v[132:133], v[120:121]
	s_nop 0
	v_cvt_pk_bf16_f32 v47, v122, v123
	v_lshlrev_b32_e32 v120, 16, v48
	v_and_b32_e32 v121, 0xffff0000, v48
	v_lshlrev_b32_e32 v134, 16, v134
	v_lshlrev_b32_e32 v135, 16, v135
	v_pk_fma_f32 v[122:123], v[14:15], v[134:135], v[120:121]
	s_nop 0
	v_cvt_pk_bf16_f32 v48, v122, v123
	v_lshlrev_b32_e32 v120, 16, v43
	v_and_b32_e32 v121, 0xffff0000, v43
	v_lshlrev_b32_e32 v136, 16, v136
	v_lshlrev_b32_e32 v137, 16, v137
	v_pk_fma_f32 v[122:123], v[8:9], v[136:137], v[120:121]
	s_nop 0
	v_cvt_pk_bf16_f32 v43, v122, v123
	v_lshlrev_b32_e32 v120, 16, v55
	v_and_b32_e32 v121, 0xffff0000, v55
	v_lshlrev_b32_e32 v138, 16, v138
	v_lshlrev_b32_e32 v139, 16, v139
	v_pk_fma_f32 v[122:123], v[10:11], v[138:139], v[120:121]
	s_nop 0
	v_cvt_pk_bf16_f32 v55, v122, v123
	s_or_b64 exec, exec, s[16:17]
	s_and_saveexec_b64 s[16:17], s[0:1]
	s_cbranch_execz .LBB0_4984
	s_branch .LBB0_4998

; DI float bf2f(bfr b) { return __uint_as_float(((unsigned)b) << 16); }
; template <int NF>
; DI void merge_tile(const Params& p, int layer, int brow, int bcol, bool& first, bool hasNext, int nbrow, int nbcol) {
;     ...
;     for (int m = 0; m < 4; ++m) {
;       const int row0 = brow + wr * 64 + m * 16 + fq * 4;
;       if (row0 < ROWS) {
; #pragma unroll
;         for (int n = 0; n < NF; ++n) {
;           const int col = bcol + wc * (NF * 16) + n * 16 + fr;
;           const bfr* gp = gmb + (long)row0 * 3072 + br * 1024 + col;
;           const float g0 = bf2f(gp[0]), g1 = bf2f(gp[3072]), g2 = bf2f(gp[2 * 3072]), g3 = bf2f(gp[3 * 3072]);
;           const unsigned t0 = tot[m][n][0], t1 = tot[m][n][1];
;           tot[m][n][0] = pack2(__uint_as_float(t0 << 16) + g0 * acc[m][n][0], __uint_as_float(t0 & 0xFFFF0000u) + g1 * acc[m][n][1]);
;           tot[m][n][1] = pack2(__uint_as_float(t1 << 16) + g2 * acc[m][n][2], __uint_as_float(t1 & 0xFFFF0000u) + g3 * acc[m][n][3]);
;         }
;       }
;     }
.LBB0_4996:
	v_lshl_add_u64 v[110:111], v[36:37], 0, s[14:15]
	v_add_co_u32_e32 v112, vcc, 0xfe9c000, v110
	s_nop 1
	v_addc_co_u32_e32 v113, vcc, 0, v111, vcc
	v_add_co_u32_e32 v114, vcc, 0xfe9e000, v110
	s_nop 1
	v_addc_co_u32_e32 v115, vcc, 0, v111, vcc
	v_add_co_u32_e32 v116, vcc, s88, v110
	s_nop 1
	v_addc_co_u32_e32 v117, vcc, 0, v111, vcc
	v_add_co_u32_e32 v118, vcc, s93, v110
	s_nop 1
	v_addc_co_u32_e32 v119, vcc, 0, v111, vcc
	global_load_ushort v132, v[112:113], off offset:3072
	global_load_ushort v133, v[114:115], off offset:1024
	global_load_ushort v134, v[116:117], off offset:3072
	global_load_ushort v135, v[118:119], off offset:1024
	global_load_ushort v136, v[112:113], off offset:3104
	global_load_ushort v137, v[114:115], off offset:1056
	global_load_ushort v138, v[116:117], off offset:3104
	global_load_ushort v139, v[118:119], off offset:1056
	s_waitcnt vmcnt(0)
	v_lshlrev_b32_e32 v120, 16, v50
	v_and_b32_e32 v121, 0xffff0000, v50
	v_lshlrev_b32_e32 v132, 16, v132
	v_lshlrev_b32_e32 v133, 16, v133
	v_pk_fma_f32 v[122:123], v[20:21], v[132:133], v[120:121]
	s_nop 0
	v_cvt_pk_bf16_f32 v50, v122, v123
	v_lshlrev_b32_e32 v120, 16, v51
	v_and_b32_e32 v121, 0xffff0000, v51
	v_lshlrev_b32_e32 v134, 16, v134
	v_lshlrev_b32_e32 v135, 16, v135
	v_pk_fma_f32 v[122:123], v[22:23], v[134:135], v[120:121]
	s_nop 0
	v_cvt_pk_bf16_f32 v51, v122, v123
	v_lshlrev_b32_e32 v120, 16, v46
	v_and_b32_e32 v121, 0xffff0000, v46
	v_lshlrev_b32_e32 v136, 16, v136
	v_lshlrev_b32_e32 v137, 16, v137
	v_pk_fma_f32 v[122:123], v[16:17], v[136:137], v[120:121]
	s_nop 0
	v_cvt_pk_bf16_f32 v46, v122, v123
	v_lshlrev_b32_e32 v120, 16, v56
	v_and_b32_e32 v121, 0xffff0000, v56
	v_lshlrev_b32_e32 v138, 16, v138
	v_lshlrev_b32_e32 v139, 16, v139
	v_pk_fma_f32 v[122:123], v[18:19], v[138:139], v[120:121]
	s_nop 0
	v_cvt_pk_bf16_f32 v56, v122, v123
	s_or_b64 exec, exec, s[16:17]
	s_and_saveexec_b64 s[16:17], s[2:3]
	s_cbranch_execnz .LBB0_4994

; DI float bf2f(bfr b) { return __uint_as_float(((unsigned)b) << 16); }
; template <int NF>
; DI void merge_tile(const Params& p, int layer, int brow, int bcol, bool& first, bool hasNext, int nbrow, int nbcol) {
;     ...
;     for (int m = 0; m < 4; ++m) {
;       const int row0 = brow + wr * 64 + m * 16 + fq * 4;
;       if (row0 < ROWS) {
; #pragma unroll
;         for (int n = 0; n < NF; ++n) {
;           const int col = bcol + wc * (NF * 16) + n * 16 + fr;
;           const bfr* gp = gmb + (long)row0 * 3072 + br * 1024 + col;
;           const float g0 = bf2f(gp[0]), g1 = bf2f(gp[3072]), g2 = bf2f(gp[2 * 3072]), g3 = bf2f(gp[3 * 3072]);
;           const unsigned t0 = tot[m][n][0], t1 = tot[m][n][1];
;           tot[m][n][0] = pack2(__uint_as_float(t0 << 16) + g0 * acc[m][n][0], __uint_as_float(t0 & 0xFFFF0000u) + g1 * acc[m][n][1]);
;           tot[m][n][1] = pack2(__uint_as_float(t1 << 16) + g2 * acc[m][n][2], __uint_as_float(t1 & 0xFFFF0000u) + g3 * acc[m][n][3]);
;         }
;       }
;     }
.LBB0_4998:
	v_lshl_add_u64 v[110:111], v[40:41], 0, s[14:15]
	v_add_co_u32_e32 v112, vcc, 0xfe9c000, v110
	s_nop 1
	v_addc_co_u32_e32 v113, vcc, 0, v111, vcc
	v_add_co_u32_e32 v114, vcc, 0xfe9e000, v110
	s_nop 1
	v_addc_co_u32_e32 v115, vcc, 0, v111, vcc
	v_add_co_u32_e32 v116, vcc, s88, v110
	s_nop 1
	v_addc_co_u32_e32 v117, vcc, 0, v111, vcc
	v_add_co_u32_e32 v118, vcc, s93, v110
	s_nop 1
	v_addc_co_u32_e32 v119, vcc, 0, v111, vcc
	global_load_ushort v132, v[112:113], off offset:3072
	global_load_ushort v133, v[114:115], off offset:1024
	global_load_ushort v134, v[116:117], off offset:3072
	global_load_ushort v135, v[118:119], off offset:1024
	global_load_ushort v136, v[112:113], off offset:3104
	global_load_ushort v137, v[114:115], off offset:1056
	global_load_ushort v138, v[116:117], off offset:3104
	global_load_ushort v139, v[118:119], off offset:1056
	s_waitcnt vmcnt(0)
	v_lshlrev_b32_e32 v120, 16, v44
	v_and_b32_e32 v121, 0xffff0000, v44
	v_lshlrev_b32_e32 v132, 16, v132
	v_lshlrev_b32_e32 v133, 16, v133
	v_pk_fma_f32 v[122:123], v[4:5], v[132:133], v[120:121]
	s_nop 0
	v_cvt_pk_bf16_f32 v44, v122, v123
	v_lshlrev_b32_e32 v120, 16, v45
	v_and_b32_e32 v121, 0xffff0000, v45
	v_lshlrev_b32_e32 v134, 16, v134
	v_lshlrev_b32_e32 v135, 16, v135
	v_pk_fma_f32 v[122:123], v[6:7], v[134:135], v[120:121]
	s_nop 0
	v_cvt_pk_bf16_f32 v45, v122, v123
	v_lshlrev_b32_e32 v120, 16, v42
	v_and_b32_e32 v121, 0xffff0000, v42
	v_lshlrev_b32_e32 v136, 16, v136
	v_lshlrev_b32_e32 v137, 16, v137
	v_pk_fma_f32 v[122:123], v[0:1], v[136:137], v[120:121]
	s_nop 0
	v_cvt_pk_bf16_f32 v42, v122, v123
	v_lshlrev_b32_e32 v120, 16, v54
	v_and_b32_e32 v121, 0xffff0000, v54
	v_lshlrev_b32_e32 v138, 16, v138
	v_lshlrev_b32_e32 v139, 16, v139
	v_pk_fma_f32 v[122:123], v[2:3], v[138:139], v[120:121]
	s_nop 0
	v_cvt_pk_bf16_f32 v54, v122, v123
	s_branch .LBB0_4984

;     ...
;   if (!chained || first) {
;     asm volatile("s_waitcnt vmcnt(0)" ::: "memory");
;     __syncthreads();
;     stage(0, 0);
;   }
;   const unsigned lds0 = (unsigned)(size_t)smem;
;   const unsigned sw0 = (unsigned)((fq ^ (fr & 7)) * 16), sw1 = (unsigned)(((4 + fq) ^ (fr & 7)) * 16);
;   const unsigned arow = lds0 + (wr * 64 + fr) * 128, brw = lds0 + 16384 + (wc * NF * 16 + fr) * 128;
;   for (int kt = 0; kt < nk; ++kt) {
;     asm volatile("s_waitcnt vmcnt(0)" ::: "memory");
;     __builtin_amdgcn_s_barrier();
;     if (kt + 1 < nk) stage(kt + 1, (kt + 1) & 1);
;     else if (chained && nbrow >= 0) {
;       const bfr* na = (nA ? nA : A) + (long)(nbrow + r0) * lda + cg;
;       const bfr* nb = (nBt ? nBt : Bt) + (long)(nbcol + r0) * ldb + cg;
; #pragma unroll
;       for (int i = 0; i < 4; ++i)
;         __builtin_amdgcn_global_load_lds((const unsigned*)(na + i * a32), (unsigned*)(smem + tid * 16 + i * 4096), 16, 0, 0);
; #pragma unroll
;       for (int i = 0; i < NF; ++i)
;         __builtin_amdgcn_global_load_lds((const unsigned*)(nb + i * b32), (unsigned*)(smem + 16384 + tid * 16 + i * 4096), 16, 0, 0);
;     }
;     const unsigned bo = (kt & 1) * 32768;
;     bf16x8 af[2][4], bfg[2][4];
;     if (NF == 4) {
;       asm volatile(
;           "ds_read_b128 %0, %16\n\tds_read_b128 %1, %16 offset:2048\n\tds_read_b128 %2, %16 offset:4096\n\tds_read_b128 %3, %16 offset:6144\n\t"
;           "ds_read_b128 %4, %17\n\tds_read_b128 %5, %17 offset:2048\n\tds_read_b128 %6, %17 offset:4096\n\tds_read_b128 %7, %17 offset:6144\n\t"
;           "ds_read_b128 %8, %18\n\tds_read_b128 %9, %18 offset:2048\n\tds_read_b128 %10, %18 offset:4096\n\tds_read_b128 %11, %18 offset:6144\n\t"
;           "ds_read_b128 %12, %19\n\tds_read_b128 %13, %19 offset:2048\n\tds_read_b128 %14, %19 offset:4096\n\tds_read_b128 %15, %19 offset:6144\n\t"
;           "s_waitcnt lgkmcnt(0)"
;           : "=&v"(af[0][0]), "=&v"(af[0][1]), "=&v"(af[0][2]), "=&v"(af[0][3]), "=&v"(bfg[0][0]), "=&v"(bfg[0][1]), "=&v"(bfg[0][2]), "=&v"(bfg[0][3]),
;             "=&v"(af[1][0]), "=&v"(af[1][1]), "=&v"(af[1][2]), "=&v"(af[1][3]), "=&v"(bfg[1][0]), "=&v"(bfg[1][1]), "=&v"(bfg[1][2]), "=&v"(bfg[1][3])
;           : "v"(arow + sw0 + bo), "v"(brw + sw0 + bo), "v"(arow + sw1 + bo), "v"(brw + sw1 + bo)
;           : "memory");
;     } else {
;       asm volatile(
.LBB0_5138:
	v_readlane_b32 s2, v251, 15
	v_readlane_b32 s3, v251, 16
	s_and_b64 vcc, exec, s[2:3]
	s_cbranch_vccz .LBB0_5172
	v_mov_b32_e32 v32, v158
	v_readlane_b32 s4, v251, 41
	v_mov_b32_e32 v9, v158
	v_readlane_b32 s5, v251, 42
	s_ashr_i32 s5, s4, 31
	v_ashrrev_i32_e32 v2, 3, v9
	v_xor_b32_e32 v3, v2, v9
	v_readlane_b32 s18, v251, 18
	v_readlane_b32 s20, v251, 20
	s_lshl_b64 s[4:5], s[4:5], 21
	v_add_u32_e32 v0, s18, v2
	v_lshlrev_b32_e32 v3, 4, v3
	v_add_u32_e32 v2, s20, v2
	s_add_u32 s4, s0, s4
	v_ashrrev_i32_e32 v1, 31, v0
	v_and_b32_e32 v128, 0x70, v3
	v_ashrrev_i32_e32 v3, 31, v2
	s_addc_u32 s5, s1, s5
	v_lshlrev_b64 v[0:1], 11, v[0:1]
	v_lshlrev_b64 v[2:3], 11, v[2:3]
	v_lshl_add_u64 v[0:1], s[0:1], 0, v[0:1]
	v_lshl_add_u64 v[2:3], s[4:5], 0, v[2:3]
	v_lshl_add_u32 v8, v9, 4, v169
	v_lshl_add_u64 v[0:1], v[0:1], 0, v[128:129]
	s_mov_b64 s[6:7], 0x6cc8400
	v_lshl_add_u64 v[2:3], v[2:3], 0, v[128:129]
	s_mov_b64 s[4:5], 0x23c8400
	v_readfirstlane_b32 s14, v8
	v_add_u32_e32 v13, 0x1000, v8
	v_lshl_add_u64 v[4:5], v[0:1], 0, s[6:7]
	v_lshl_add_u64 v[6:7], v[2:3], 0, s[4:5]
	s_mov_b32 m0, s14
	s_mov_b64 s[4:5], 0x6cd8400
	v_readfirstlane_b32 s3, v13
	s_waitcnt vmcnt(0)
	s_waitcnt vmcnt(0) lgkmcnt(0)
	s_barrier
	global_load_lds_dwordx4 v[4:5], off
	v_lshl_add_u64 v[4:5], v[0:1], 0, s[4:5]
	s_mov_b32 m0, s3
	s_mov_b64 s[4:5], 0x6ce8400
	v_add_u32_e32 v13, 0x2000, v8
	global_load_lds_dwordx4 v[4:5], off
	v_lshl_add_u64 v[4:5], v[0:1], 0, s[4:5]
	v_readfirstlane_b32 s4, v13
	s_mov_b32 m0, s4
	s_mov_b64 s[6:7], 0x6cf8400
	v_add_u32_e32 v13, 0x3000, v8
	global_load_lds_dwordx4 v[4:5], off
	v_lshl_add_u64 v[4:5], v[0:1], 0, s[6:7]
	v_readfirstlane_b32 s6, v13
	s_mov_b32 m0, s6
	v_readfirstlane_b32 s10, v9
	global_load_lds_dwordx4 v[4:5], off
	v_add_u32_e32 v4, 0x4000, v8
	s_mov_b64 s[8:9], 0x23d8400
	v_readfirstlane_b32 s5, v4
	s_mov_b32 m0, s5
	v_lshl_add_u64 v[4:5], v[2:3], 0, s[8:9]
	global_load_lds_dwordx4 v[6:7], off
	v_add_u32_e32 v6, 0x5000, v8
	s_lshr_b32 s8, s10, 1
	v_readfirstlane_b32 s7, v6
	s_cmp_lg_u32 0x80, -1
	v_and_b32_e32 v10, 15, v9
	s_mov_b32 m0, s7
	s_cselect_b32 s9, 0x80, 0
	global_load_lds_dwordx4 v[4:5], off
	v_and_or_b32 v4, s8, 32, v10
	s_add_i32 s10, s9, 0x4000
	s_and_b32 s8, s8, 0x1ffffc0
	v_lshl_add_u32 v7, v4, 7, s10
	v_or_b32_e32 v4, s8, v10
	v_lshrrev_b32_e32 v11, 4, v9
	v_bfe_u32 v12, v9, 4, 2
	v_lshl_add_u32 v6, v4, 7, s9
	v_and_b32_e32 v4, 7, v9
	v_bitop3_b32 v5, v12, v4, 4 bitop3:0x36
	v_bitop3_b32 v4, v11, v4, 3 bitop3:0x6c
	v_lshlrev_b32_e32 v9, 4, v5
	v_lshlrev_b32_e32 v5, 4, v4
	v_add_u32_e32 v4, v6, v5
	v_add_u32_e32 v5, v7, v5
	v_add_u32_e32 v6, v6, v9
	v_add_u32_e32 v7, v7, v9
	v_add_u32_e32 v9, 0x8000, v8
	v_lshl_add_u64 v[10:11], v[0:1], 0, s[52:53]
	v_readfirstlane_b32 s13, v9
	v_add_u32_e32 v9, 0x9000, v8
	s_mov_b32 m0, s13
	v_readfirstlane_b32 s8, v9
	v_add_u32_e32 v9, 0xa000, v8
	s_waitcnt vmcnt(0)
	s_barrier
	global_load_lds_dwordx4 v[10:11], off
	v_lshl_add_u64 v[10:11], v[0:1], 0, s[54:55]
	s_mov_b32 m0, s8
	v_readfirstlane_b32 s9, v9
	global_load_lds_dwordx4 v[10:11], off
	v_lshl_add_u64 v[10:11], v[0:1], 0, s[56:57]
	s_mov_b32 m0, s9
	s_mov_b64 s[10:11], 0x6cf8480
	v_add_u32_e32 v9, 0xb000, v8
	global_load_lds_dwordx4 v[10:11], off
	v_lshl_add_u64 v[10:11], v[0:1], 0, s[10:11]
	v_readfirstlane_b32 s10, v9
	v_add_u32_e32 v9, 0xc000, v8
	s_mov_b32 m0, s10
	s_mov_b64 s[16:17], 0x23c8480
	v_readfirstlane_b32 s11, v9
	v_add_u32_e32 v9, 0xd000, v8
	global_load_lds_dwordx4 v[10:11], off
	v_lshl_add_u64 v[10:11], v[2:3], 0, s[16:17]
	s_mov_b32 m0, s11
	s_mov_b64 s[16:17], 0x23d8480
	v_readfirstlane_b32 s12, v9
	global_load_lds_dwordx4 v[10:11], off
	v_lshl_add_u64 v[10:11], v[2:3], 0, s[16:17]
	s_mov_b32 m0, s12
	v_readfirstlane_b32 s2, v32
	global_load_lds_dwordx4 v[10:11], off
	ds_read_b128 v[10:13], v4
	ds_read_b128 v[14:17], v4 offset:2048
	ds_read_b128 v[18:21], v4 offset:4096
	ds_read_b128 v[22:25], v4 offset:6144
	ds_read_b128 v[26:29], v5
	ds_read_b128 v[34:37], v5 offset:2048
	ds_read_b128 v[38:41], v6
	ds_read_b128 v[42:45], v6 offset:2048
	ds_read_b128 v[46:49], v6 offset:4096
	ds_read_b128 v[50:53], v6 offset:6144
	ds_read_b128 v[54:57], v7
	ds_read_b128 v[58:61], v7 offset:2048
	s_waitcnt lgkmcnt(0)
	v_and_b32_e32 v33, 15, v32
	v_readlane_b32 s21, v251, 21
	s_setprio 1
	v_mfma_f32_16x16x32_bf16 v[62:65], v[10:13], v[26:29], 0
	v_mfma_f32_16x16x32_bf16 v[66:69], v[14:17], v[26:29], 0
	v_mfma_f32_16x16x32_bf16 v[14:17], v[14:17], v[34:37], 0
	v_mfma_f32_16x16x32_bf16 v[70:73], v[18:21], v[26:29], 0
	v_mfma_f32_16x16x32_bf16 v[18:21], v[18:21], v[34:37], 0
	v_mfma_f32_16x16x32_bf16 v[26:29], v[22:25], v[26:29], 0
	v_mfma_f32_16x16x32_bf16 v[22:25], v[22:25], v[34:37], 0
	v_mfma_f32_16x16x32_bf16 v[10:13], v[10:13], v[34:37], 0
	v_mfma_f32_16x16x32_bf16 v[34:37], v[38:41], v[54:57], v[62:65]
	v_mfma_f32_16x16x32_bf16 v[14:17], v[42:45], v[58:61], v[14:17]
	v_mfma_f32_16x16x32_bf16 v[18:21], v[46:49], v[58:61], v[18:21]
	v_mfma_f32_16x16x32_bf16 v[26:29], v[50:53], v[54:57], v[26:29]
	v_mfma_f32_16x16x32_bf16 v[22:25], v[50:53], v[58:61], v[22:25]
	v_mfma_f32_16x16x32_bf16 v[38:41], v[38:41], v[58:61], v[10:13]
	v_mfma_f32_16x16x32_bf16 v[62:65], v[42:45], v[54:57], v[66:69]
	v_mfma_f32_16x16x32_bf16 v[42:45], v[46:49], v[54:57], v[70:73]
	s_setprio 0
	s_mov_b64 s[16:17], 0x6cc8500
	s_mov_b32 m0, s14
	v_lshl_add_u64 v[10:11], v[0:1], 0, s[16:17]
	s_mov_b64 s[16:17], 0x6cd8500
	s_waitcnt vmcnt(0)
	s_barrier
;     ...
;   for (int kt = 0; kt < nk; ++kt) {
;     asm volatile("s_waitcnt vmcnt(0)" ::: "memory");
;     __builtin_amdgcn_s_barrier();
;     if (kt + 1 < nk) stage(kt + 1, (kt + 1) & 1);
;     else if (chained && nbrow >= 0) {
;       const bfr* na = (nA ? nA : A) + (long)(nbrow + r0) * lda + cg;
;       const bfr* nb = (nBt ? nBt : Bt) + (long)(nbcol + r0) * ldb + cg;
; #pragma unroll
;       for (int i = 0; i < 4; ++i)
;         __builtin_amdgcn_global_load_lds((const unsigned*)(na + i * a32), (unsigned*)(smem + tid * 16 + i * 4096), 16, 0, 0);
; #pragma unroll
;       for (int i = 0; i < NF; ++i)
;         __builtin_amdgcn_global_load_lds((const unsigned*)(nb + i * b32), (unsigned*)(smem + 16384 + tid * 16 + i * 4096), 16, 0, 0);
;     }
;     const unsigned bo = (kt & 1) * 32768;
;     bf16x8 af[2][4], bfg[2][4];
;     if (NF == 4) {
;       asm volatile(
;           "ds_read_b128 %0, %16\n\tds_read_b128 %1, %16 offset:2048\n\tds_read_b128 %2, %16 offset:4096\n\tds_read_b128 %3, %16 offset:6144\n\t"
;           "ds_read_b128 %4, %17\n\tds_read_b128 %5, %17 offset:2048\n\tds_read_b128 %6, %17 offset:4096\n\tds_read_b128 %7, %17 offset:6144\n\t"
;           "ds_read_b128 %8, %18\n\tds_read_b128 %9, %18 offset:2048\n\tds_read_b128 %10, %18 offset:4096\n\tds_read_b128 %11, %18 offset:6144\n\t"
;           "ds_read_b128 %12, %19\n\tds_read_b128 %13, %19 offset:2048\n\tds_read_b128 %14, %19 offset:4096\n\tds_read_b128 %15, %19 offset:6144\n\t"
;           "s_waitcnt lgkmcnt(0)"
;           : "=&v"(af[0][0]), "=&v"(af[0][1]), "=&v"(af[0][2]), "=&v"(af[0][3]), "=&v"(bfg[0][0]), "=&v"(bfg[0][1]), "=&v"(bfg[0][2]), "=&v"(bfg[0][3]),
;             "=&v"(af[1][0]), "=&v"(af[1][1]), "=&v"(af[1][2]), "=&v"(af[1][3]), "=&v"(bfg[1][0]), "=&v"(bfg[1][1]), "=&v"(bfg[1][2]), "=&v"(bfg[1][3])
;           : "v"(arow + sw0 + bo), "v"(brw + sw0 + bo), "v"(arow + sw1 + bo), "v"(brw + sw1 + bo)
;           : "memory");
;     } else {
;       asm volatile(
;           "ds_read_b128 %0, %12\n\tds_read_b128 %1, %12 offset:2048\n\tds_read_b128 %2, %12 offset:4096\n\tds_read_b128 %3, %12 offset:6144\n\t"
;           "ds_read_b128 %4, %13\n\tds_read_b128 %5, %13 offset:2048\n\t"
;           "ds_read_b128 %6, %14\n\tds_read_b128 %7, %14 offset:2048\n\tds_read_b128 %8, %14 offset:4096\n\tds_read_b128 %9, %14 offset:6144\n\t"
	global_load_lds_dwordx4 v[10:11], off
	v_lshl_add_u64 v[10:11], v[0:1], 0, s[16:17]
	s_mov_b32 m0, s3
	s_mov_b64 s[16:17], 0x6ce8500
	global_load_lds_dwordx4 v[10:11], off
	v_lshl_add_u64 v[10:11], v[0:1], 0, s[16:17]
	s_mov_b32 m0, s4
	s_mov_b64 s[16:17], 0x6cf8500
	global_load_lds_dwordx4 v[10:11], off
	v_lshl_add_u64 v[10:11], v[0:1], 0, s[16:17]
	s_mov_b32 m0, s6
	s_mov_b64 s[16:17], 0x23c8500
	global_load_lds_dwordx4 v[10:11], off
	v_lshl_add_u64 v[10:11], v[2:3], 0, s[16:17]
	s_mov_b32 m0, s5
	s_mov_b64 s[16:17], 0x23d8500
	global_load_lds_dwordx4 v[10:11], off
	v_lshl_add_u64 v[10:11], v[2:3], 0, s[16:17]
	s_mov_b32 m0, s7
	v_add_u32_e32 v9, 0x8000, v4
	global_load_lds_dwordx4 v[10:11], off
	v_add_u32_e32 v10, 0x8000, v5
	v_add_u32_e32 v11, 0x8000, v6
	v_add_u32_e32 v12, 0x8000, v7
	ds_read_b128 v[46:49], v9
	ds_read_b128 v[50:53], v9 offset:2048
	ds_read_b128 v[54:57], v9 offset:4096
	ds_read_b128 v[58:61], v9 offset:6144
	ds_read_b128 v[66:69], v10
	ds_read_b128 v[70:73], v10 offset:2048
	ds_read_b128 v[74:77], v11
	ds_read_b128 v[78:81], v11 offset:2048
	ds_read_b128 v[82:85], v11 offset:4096
	ds_read_b128 v[86:89], v11 offset:6144
	ds_read_b128 v[90:93], v12
	ds_read_b128 v[94:97], v12 offset:2048
	s_waitcnt lgkmcnt(0)
	s_setprio 1
	v_mfma_f32_16x16x32_bf16 v[34:37], v[46:49], v[66:69], v[34:37]
	v_mfma_f32_16x16x32_bf16 v[14:17], v[50:53], v[70:73], v[14:17]
	v_mfma_f32_16x16x32_bf16 v[18:21], v[54:57], v[70:73], v[18:21]
	v_mfma_f32_16x16x32_bf16 v[26:29], v[58:61], v[66:69], v[26:29]
	v_mfma_f32_16x16x32_bf16 v[22:25], v[58:61], v[70:73], v[22:25]
	v_mfma_f32_16x16x32_bf16 v[38:41], v[46:49], v[70:73], v[38:41]
	v_mfma_f32_16x16x32_bf16 v[46:49], v[50:53], v[66:69], v[62:65]
	v_mfma_f32_16x16x32_bf16 v[42:45], v[54:57], v[66:69], v[42:45]
	v_mfma_f32_16x16x32_bf16 v[34:37], v[74:77], v[90:93], v[34:37]
	v_mfma_f32_16x16x32_bf16 v[14:17], v[78:81], v[94:97], v[14:17]
	v_mfma_f32_16x16x32_bf16 v[18:21], v[82:85], v[94:97], v[18:21]
	v_mfma_f32_16x16x32_bf16 v[26:29], v[86:89], v[90:93], v[26:29]
	v_mfma_f32_16x16x32_bf16 v[22:25], v[86:89], v[94:97], v[22:25]
	v_mfma_f32_16x16x32_bf16 v[38:41], v[74:77], v[94:97], v[38:41]
	v_mfma_f32_16x16x32_bf16 v[46:49], v[78:81], v[90:93], v[46:49]
	v_mfma_f32_16x16x32_bf16 v[42:45], v[82:85], v[90:93], v[42:45]
	s_setprio 0
	s_mov_b64 s[16:17], 0x6cc8580
	s_mov_b32 m0, s13
	v_lshl_add_u64 v[30:31], v[0:1], 0, s[16:17]
	s_mov_b64 s[16:17], 0x6cd8580
	s_waitcnt vmcnt(0)
	s_barrier
	global_load_lds_dwordx4 v[30:31], off
	v_lshl_add_u64 v[30:31], v[0:1], 0, s[16:17]
	s_mov_b32 m0, s8
	s_mov_b64 s[16:17], 0x6ce8580
	global_load_lds_dwordx4 v[30:31], off
	v_lshl_add_u64 v[30:31], v[0:1], 0, s[16:17]
	s_mov_b32 m0, s9
	s_mov_b64 s[16:17], 0x6cf8580
	global_load_lds_dwordx4 v[30:31], off
	v_lshl_add_u64 v[30:31], v[0:1], 0, s[16:17]
	s_mov_b32 m0, s10
	s_mov_b64 s[16:17], 0x23c8580
	global_load_lds_dwordx4 v[30:31], off
	v_lshl_add_u64 v[30:31], v[2:3], 0, s[16:17]
	s_mov_b32 m0, s11
	s_mov_b64 s[16:17], 0x23d8580
	global_load_lds_dwordx4 v[30:31], off
	v_lshl_add_u64 v[30:31], v[2:3], 0, s[16:17]
	s_mov_b32 m0, s12
	s_nop 0
	global_load_lds_dwordx4 v[30:31], off
	ds_read_b128 v[50:53], v4
	ds_read_b128 v[54:57], v4 offset:2048
	ds_read_b128 v[58:61], v4 offset:4096
	ds_read_b128 v[62:65], v4 offset:6144
	ds_read_b128 v[66:69], v5
	ds_read_b128 v[70:73], v5 offset:2048
	ds_read_b128 v[74:77], v6
	ds_read_b128 v[78:81], v6 offset:2048
	ds_read_b128 v[82:85], v6 offset:4096
	ds_read_b128 v[86:89], v6 offset:6144
	ds_read_b128 v[90:93], v7
	ds_read_b128 v[94:97], v7 offset:2048
	s_waitcnt lgkmcnt(0)
	s_setprio 1
	v_mfma_f32_16x16x32_bf16 v[34:37], v[50:53], v[66:69], v[34:37]
	v_mfma_f32_16x16x32_bf16 v[14:17], v[54:57], v[70:73], v[14:17]
	v_mfma_f32_16x16x32_bf16 v[18:21], v[58:61], v[70:73], v[18:21]
	v_mfma_f32_16x16x32_bf16 v[26:29], v[62:65], v[66:69], v[26:29]
	v_mfma_f32_16x16x32_bf16 v[22:25], v[62:65], v[70:73], v[22:25]
	v_mfma_f32_16x16x32_bf16 v[38:41], v[50:53], v[70:73], v[38:41]
	v_mfma_f32_16x16x32_bf16 v[46:49], v[54:57], v[66:69], v[46:49]
	v_mfma_f32_16x16x32_bf16 v[42:45], v[58:61], v[66:69], v[42:45]
	v_mfma_f32_16x16x32_bf16 v[34:37], v[74:77], v[90:93], v[34:37]
	v_mfma_f32_16x16x32_bf16 v[14:17], v[78:81], v[94:97], v[14:17]
	v_mfma_f32_16x16x32_bf16 v[18:21], v[82:85], v[94:97], v[18:21]
	v_mfma_f32_16x16x32_bf16 v[26:29], v[86:89], v[90:93], v[26:29]
	v_mfma_f32_16x16x32_bf16 v[22:25], v[86:89], v[94:97], v[22:25]
	v_mfma_f32_16x16x32_bf16 v[38:41], v[74:77], v[94:97], v[38:41]
	v_mfma_f32_16x16x32_bf16 v[46:49], v[78:81], v[90:93], v[46:49]
	v_mfma_f32_16x16x32_bf16 v[42:45], v[82:85], v[90:93], v[42:45]
	s_setprio 0
	s_mov_b64 s[16:17], 0x6cc8600
	s_mov_b32 m0, s14
	v_lshl_add_u64 v[30:31], v[0:1], 0, s[16:17]
	s_mov_b64 s[16:17], 0x6cd8600
	s_waitcnt vmcnt(0)
	s_barrier
;     ...
;   for (int kt = 0; kt < nk; ++kt) {
;     asm volatile("s_waitcnt vmcnt(0)" ::: "memory");
;     __builtin_amdgcn_s_barrier();
;     if (kt + 1 < nk) stage(kt + 1, (kt + 1) & 1);
;     else if (chained && nbrow >= 0) {
;       const bfr* na = (nA ? nA : A) + (long)(nbrow + r0) * lda + cg;
;       const bfr* nb = (nBt ? nBt : Bt) + (long)(nbcol + r0) * ldb + cg;
; #pragma unroll
;       for (int i = 0; i < 4; ++i)
;         __builtin_amdgcn_global_load_lds((const unsigned*)(na + i * a32), (unsigned*)(smem + tid * 16 + i * 4096), 16, 0, 0);
; #pragma unroll
;       for (int i = 0; i < NF; ++i)
;         __builtin_amdgcn_global_load_lds((const unsigned*)(nb + i * b32), (unsigned*)(smem + 16384 + tid * 16 + i * 4096), 16, 0, 0);
;     }
;     const unsigned bo = (kt & 1) * 32768;
;     bf16x8 af[2][4], bfg[2][4];
;     if (NF == 4) {
;       asm volatile(
;           "ds_read_b128 %0, %16\n\tds_read_b128 %1, %16 offset:2048\n\tds_read_b128 %2, %16 offset:4096\n\tds_read_b128 %3, %16 offset:6144\n\t"
;           "ds_read_b128 %4, %17\n\tds_read_b128 %5, %17 offset:2048\n\tds_read_b128 %6, %17 offset:4096\n\tds_read_b128 %7, %17 offset:6144\n\t"
;           "ds_read_b128 %8, %18\n\tds_read_b128 %9, %18 offset:2048\n\tds_read_b128 %10, %18 offset:4096\n\tds_read_b128 %11, %18 offset:6144\n\t"
;           "ds_read_b128 %12, %19\n\tds_read_b128 %13, %19 offset:2048\n\tds_read_b128 %14, %19 offset:4096\n\tds_read_b128 %15, %19 offset:6144\n\t"
;           "s_waitcnt lgkmcnt(0)"
;           : "=&v"(af[0][0]), "=&v"(af[0][1]), "=&v"(af[0][2]), "=&v"(af[0][3]), "=&v"(bfg[0][0]), "=&v"(bfg[0][1]), "=&v"(bfg[0][2]), "=&v"(bfg[0][3]),
;             "=&v"(af[1][0]), "=&v"(af[1][1]), "=&v"(af[1][2]), "=&v"(af[1][3]), "=&v"(bfg[1][0]), "=&v"(bfg[1][1]), "=&v"(bfg[1][2]), "=&v"(bfg[1][3])
;           : "v"(arow + sw0 + bo), "v"(brw + sw0 + bo), "v"(arow + sw1 + bo), "v"(brw + sw1 + bo)
;           : "memory");
;     } else {
;       asm volatile(
;           "ds_read_b128 %0, %12\n\tds_read_b128 %1, %12 offset:2048\n\tds_read_b128 %2, %12 offset:4096\n\tds_read_b128 %3, %12 offset:6144\n\t"
;           "ds_read_b128 %4, %13\n\tds_read_b128 %5, %13 offset:2048\n\t"
;           "ds_read_b128 %6, %14\n\tds_read_b128 %7, %14 offset:2048\n\tds_read_b128 %8, %14 offset:4096\n\tds_read_b128 %9, %14 offset:6144\n\t"
	global_load_lds_dwordx4 v[30:31], off
	v_lshl_add_u64 v[30:31], v[0:1], 0, s[16:17]
	s_mov_b32 m0, s3
	s_mov_b64 s[16:17], 0x6ce8600
	global_load_lds_dwordx4 v[30:31], off
	v_lshl_add_u64 v[30:31], v[0:1], 0, s[16:17]
	s_mov_b32 m0, s4
	s_mov_b64 s[16:17], 0x6cf8600
	global_load_lds_dwordx4 v[30:31], off
	v_lshl_add_u64 v[30:31], v[0:1], 0, s[16:17]
	s_mov_b32 m0, s6
	s_mov_b64 s[16:17], 0x23c8600
	global_load_lds_dwordx4 v[30:31], off
	v_lshl_add_u64 v[30:31], v[2:3], 0, s[16:17]
	s_mov_b32 m0, s5
	s_mov_b64 s[16:17], 0x23d8600
	global_load_lds_dwordx4 v[30:31], off
	v_lshl_add_u64 v[30:31], v[2:3], 0, s[16:17]
	s_mov_b32 m0, s7
	s_nop 0
	global_load_lds_dwordx4 v[30:31], off
	ds_read_b128 v[50:53], v9
	ds_read_b128 v[54:57], v9 offset:2048
	ds_read_b128 v[58:61], v9 offset:4096
	ds_read_b128 v[62:65], v9 offset:6144
	ds_read_b128 v[66:69], v10
	ds_read_b128 v[70:73], v10 offset:2048
	ds_read_b128 v[74:77], v11
	ds_read_b128 v[78:81], v11 offset:2048
	ds_read_b128 v[82:85], v11 offset:4096
	ds_read_b128 v[86:89], v11 offset:6144
	ds_read_b128 v[90:93], v12
	ds_read_b128 v[94:97], v12 offset:2048
	s_waitcnt lgkmcnt(0)
	s_setprio 1
	v_mfma_f32_16x16x32_bf16 v[34:37], v[50:53], v[66:69], v[34:37]
	v_mfma_f32_16x16x32_bf16 v[14:17], v[54:57], v[70:73], v[14:17]
	v_mfma_f32_16x16x32_bf16 v[18:21], v[58:61], v[70:73], v[18:21]
	v_mfma_f32_16x16x32_bf16 v[26:29], v[62:65], v[66:69], v[26:29]
	v_mfma_f32_16x16x32_bf16 v[22:25], v[62:65], v[70:73], v[22:25]
	v_mfma_f32_16x16x32_bf16 v[38:41], v[50:53], v[70:73], v[38:41]
	v_mfma_f32_16x16x32_bf16 v[46:49], v[54:57], v[66:69], v[46:49]
	v_mfma_f32_16x16x32_bf16 v[42:45], v[58:61], v[66:69], v[42:45]
	v_mfma_f32_16x16x32_bf16 v[34:37], v[74:77], v[90:93], v[34:37]
	v_mfma_f32_16x16x32_bf16 v[14:17], v[78:81], v[94:97], v[14:17]
	v_mfma_f32_16x16x32_bf16 v[18:21], v[82:85], v[94:97], v[18:21]
	v_mfma_f32_16x16x32_bf16 v[26:29], v[86:89], v[90:93], v[26:29]
	v_mfma_f32_16x16x32_bf16 v[22:25], v[86:89], v[94:97], v[22:25]
	v_mfma_f32_16x16x32_bf16 v[38:41], v[74:77], v[94:97], v[38:41]
	v_mfma_f32_16x16x32_bf16 v[46:49], v[78:81], v[90:93], v[46:49]
	v_mfma_f32_16x16x32_bf16 v[42:45], v[82:85], v[90:93], v[42:45]
	s_setprio 0
	s_mov_b64 s[16:17], 0x6cc8680
	s_mov_b32 m0, s13
	v_lshl_add_u64 v[30:31], v[0:1], 0, s[16:17]
	s_mov_b64 s[16:17], 0x6cd8680
	s_waitcnt vmcnt(0)
	s_barrier
	global_load_lds_dwordx4 v[30:31], off
	v_lshl_add_u64 v[30:31], v[0:1], 0, s[16:17]
	s_mov_b32 m0, s8
	s_mov_b64 s[16:17], 0x6ce8680
	global_load_lds_dwordx4 v[30:31], off
	v_lshl_add_u64 v[30:31], v[0:1], 0, s[16:17]
	s_mov_b32 m0, s9
	s_mov_b64 s[16:17], 0x6cf8680
	global_load_lds_dwordx4 v[30:31], off
	v_lshl_add_u64 v[30:31], v[0:1], 0, s[16:17]
	s_mov_b32 m0, s10
	s_mov_b64 s[16:17], 0x23c8680
	global_load_lds_dwordx4 v[30:31], off
	v_lshl_add_u64 v[30:31], v[2:3], 0, s[16:17]
	s_mov_b32 m0, s11
	s_mov_b64 s[16:17], 0x23d8680
	global_load_lds_dwordx4 v[30:31], off
	v_lshl_add_u64 v[30:31], v[2:3], 0, s[16:17]
	s_mov_b32 m0, s12
	s_nop 0
	global_load_lds_dwordx4 v[30:31], off
	ds_read_b128 v[50:53], v4
	ds_read_b128 v[54:57], v4 offset:2048
	ds_read_b128 v[58:61], v4 offset:4096
	ds_read_b128 v[62:65], v4 offset:6144
	ds_read_b128 v[66:69], v5
	ds_read_b128 v[70:73], v5 offset:2048
	ds_read_b128 v[74:77], v6
	ds_read_b128 v[78:81], v6 offset:2048
	ds_read_b128 v[82:85], v6 offset:4096
	ds_read_b128 v[86:89], v6 offset:6144
	ds_read_b128 v[90:93], v7
	ds_read_b128 v[94:97], v7 offset:2048
	s_waitcnt lgkmcnt(0)
	s_setprio 1
	v_mfma_f32_16x16x32_bf16 v[34:37], v[50:53], v[66:69], v[34:37]
	v_mfma_f32_16x16x32_bf16 v[14:17], v[54:57], v[70:73], v[14:17]
	v_mfma_f32_16x16x32_bf16 v[18:21], v[58:61], v[70:73], v[18:21]
	v_mfma_f32_16x16x32_bf16 v[26:29], v[62:65], v[66:69], v[26:29]
	v_mfma_f32_16x16x32_bf16 v[22:25], v[62:65], v[70:73], v[22:25]
	v_mfma_f32_16x16x32_bf16 v[38:41], v[50:53], v[70:73], v[38:41]
	v_mfma_f32_16x16x32_bf16 v[46:49], v[54:57], v[66:69], v[46:49]
	v_mfma_f32_16x16x32_bf16 v[42:45], v[58:61], v[66:69], v[42:45]
	v_mfma_f32_16x16x32_bf16 v[34:37], v[74:77], v[90:93], v[34:37]
	v_mfma_f32_16x16x32_bf16 v[14:17], v[78:81], v[94:97], v[14:17]
	v_mfma_f32_16x16x32_bf16 v[18:21], v[82:85], v[94:97], v[18:21]
	v_mfma_f32_16x16x32_bf16 v[26:29], v[86:89], v[90:93], v[26:29]
	v_mfma_f32_16x16x32_bf16 v[22:25], v[86:89], v[94:97], v[22:25]
	v_mfma_f32_16x16x32_bf16 v[38:41], v[74:77], v[94:97], v[38:41]
	v_mfma_f32_16x16x32_bf16 v[46:49], v[78:81], v[90:93], v[46:49]
	v_mfma_f32_16x16x32_bf16 v[42:45], v[82:85], v[90:93], v[42:45]
	s_setprio 0
	s_mov_b64 s[16:17], 0x6cc8700
	s_mov_b32 m0, s14
	v_lshl_add_u64 v[30:31], v[0:1], 0, s[16:17]
	s_mov_b64 s[16:17], 0x6cd8700
	s_waitcnt vmcnt(0)
	s_barrier
;     ...
;   for (int kt = 0; kt < nk; ++kt) {
;     asm volatile("s_waitcnt vmcnt(0)" ::: "memory");
;     __builtin_amdgcn_s_barrier();
;     if (kt + 1 < nk) stage(kt + 1, (kt + 1) & 1);
;     else if (chained && nbrow >= 0) {
;       const bfr* na = (nA ? nA : A) + (long)(nbrow + r0) * lda + cg;
;       const bfr* nb = (nBt ? nBt : Bt) + (long)(nbcol + r0) * ldb + cg;
; #pragma unroll
;       for (int i = 0; i < 4; ++i)
;         __builtin_amdgcn_global_load_lds((const unsigned*)(na + i * a32), (unsigned*)(smem + tid * 16 + i * 4096), 16, 0, 0);
; #pragma unroll
;       for (int i = 0; i < NF; ++i)
;         __builtin_amdgcn_global_load_lds((const unsigned*)(nb + i * b32), (unsigned*)(smem + 16384 + tid * 16 + i * 4096), 16, 0, 0);
;     }
;     const unsigned bo = (kt & 1) * 32768;
;     bf16x8 af[2][4], bfg[2][4];
;     if (NF == 4) {
;       asm volatile(
;           "ds_read_b128 %0, %16\n\tds_read_b128 %1, %16 offset:2048\n\tds_read_b128 %2, %16 offset:4096\n\tds_read_b128 %3, %16 offset:6144\n\t"
;           "ds_read_b128 %4, %17\n\tds_read_b128 %5, %17 offset:2048\n\tds_read_b128 %6, %17 offset:4096\n\tds_read_b128 %7, %17 offset:6144\n\t"
;           "ds_read_b128 %8, %18\n\tds_read_b128 %9, %18 offset:2048\n\tds_read_b128 %10, %18 offset:4096\n\tds_read_b128 %11, %18 offset:6144\n\t"
;           "ds_read_b128 %12, %19\n\tds_read_b128 %13, %19 offset:2048\n\tds_read_b128 %14, %19 offset:4096\n\tds_read_b128 %15, %19 offset:6144\n\t"
;           "s_waitcnt lgkmcnt(0)"
;           : "=&v"(af[0][0]), "=&v"(af[0][1]), "=&v"(af[0][2]), "=&v"(af[0][3]), "=&v"(bfg[0][0]), "=&v"(bfg[0][1]), "=&v"(bfg[0][2]), "=&v"(bfg[0][3]),
;             "=&v"(af[1][0]), "=&v"(af[1][1]), "=&v"(af[1][2]), "=&v"(af[1][3]), "=&v"(bfg[1][0]), "=&v"(bfg[1][1]), "=&v"(bfg[1][2]), "=&v"(bfg[1][3])
;           : "v"(arow + sw0 + bo), "v"(brw + sw0 + bo), "v"(arow + sw1 + bo), "v"(brw + sw1 + bo)
;           : "memory");
;     } else {
;       asm volatile(
;           "ds_read_b128 %0, %12\n\tds_read_b128 %1, %12 offset:2048\n\tds_read_b128 %2, %12 offset:4096\n\tds_read_b128 %3, %12 offset:6144\n\t"
;           "ds_read_b128 %4, %13\n\tds_read_b128 %5, %13 offset:2048\n\t"
;           "ds_read_b128 %6, %14\n\tds_read_b128 %7, %14 offset:2048\n\tds_read_b128 %8, %14 offset:4096\n\tds_read_b128 %9, %14 offset:6144\n\t"
	global_load_lds_dwordx4 v[30:31], off
	v_lshl_add_u64 v[30:31], v[0:1], 0, s[16:17]
	s_mov_b32 m0, s3
	s_mov_b64 s[16:17], 0x6ce8700
	global_load_lds_dwordx4 v[30:31], off
	v_lshl_add_u64 v[30:31], v[0:1], 0, s[16:17]
	s_mov_b32 m0, s4
	s_mov_b64 s[16:17], 0x6cf8700
	global_load_lds_dwordx4 v[30:31], off
	v_lshl_add_u64 v[30:31], v[0:1], 0, s[16:17]
	s_mov_b32 m0, s6
	s_mov_b64 s[16:17], 0x23c8700
	global_load_lds_dwordx4 v[30:31], off
	v_lshl_add_u64 v[30:31], v[2:3], 0, s[16:17]
	s_mov_b32 m0, s5
	s_mov_b64 s[16:17], 0x23d8700
	global_load_lds_dwordx4 v[30:31], off
	v_lshl_add_u64 v[30:31], v[2:3], 0, s[16:17]
	s_mov_b32 m0, s7
	s_nop 0
	global_load_lds_dwordx4 v[30:31], off
	ds_read_b128 v[50:53], v9
	ds_read_b128 v[54:57], v9 offset:2048
	ds_read_b128 v[58:61], v9 offset:4096
	ds_read_b128 v[62:65], v9 offset:6144
	ds_read_b128 v[66:69], v10
	ds_read_b128 v[70:73], v10 offset:2048
	ds_read_b128 v[74:77], v11
	ds_read_b128 v[78:81], v11 offset:2048
	ds_read_b128 v[82:85], v11 offset:4096
	ds_read_b128 v[86:89], v11 offset:6144
	ds_read_b128 v[90:93], v12
	ds_read_b128 v[94:97], v12 offset:2048
	s_waitcnt lgkmcnt(0)
	s_setprio 1
	v_mfma_f32_16x16x32_bf16 v[34:37], v[50:53], v[66:69], v[34:37]
	v_mfma_f32_16x16x32_bf16 v[14:17], v[54:57], v[70:73], v[14:17]
	v_mfma_f32_16x16x32_bf16 v[18:21], v[58:61], v[70:73], v[18:21]
	v_mfma_f32_16x16x32_bf16 v[26:29], v[62:65], v[66:69], v[26:29]
	v_mfma_f32_16x16x32_bf16 v[22:25], v[62:65], v[70:73], v[22:25]
	v_mfma_f32_16x16x32_bf16 v[38:41], v[50:53], v[70:73], v[38:41]
	v_mfma_f32_16x16x32_bf16 v[46:49], v[54:57], v[66:69], v[46:49]
	v_mfma_f32_16x16x32_bf16 v[42:45], v[58:61], v[66:69], v[42:45]
	v_mfma_f32_16x16x32_bf16 v[34:37], v[74:77], v[90:93], v[34:37]
	v_mfma_f32_16x16x32_bf16 v[14:17], v[78:81], v[94:97], v[14:17]
	v_mfma_f32_16x16x32_bf16 v[18:21], v[82:85], v[94:97], v[18:21]
	v_mfma_f32_16x16x32_bf16 v[26:29], v[86:89], v[90:93], v[26:29]
	v_mfma_f32_16x16x32_bf16 v[22:25], v[86:89], v[94:97], v[22:25]
	v_mfma_f32_16x16x32_bf16 v[38:41], v[74:77], v[94:97], v[38:41]
	v_mfma_f32_16x16x32_bf16 v[46:49], v[78:81], v[90:93], v[46:49]
	v_mfma_f32_16x16x32_bf16 v[42:45], v[82:85], v[90:93], v[42:45]
	s_setprio 0
	s_mov_b64 s[16:17], 0x6cc8780
	s_mov_b32 m0, s13
	v_lshl_add_u64 v[30:31], v[0:1], 0, s[16:17]
	s_mov_b64 s[16:17], 0x6cd8780
	s_waitcnt vmcnt(0)
	s_barrier
	global_load_lds_dwordx4 v[30:31], off
	v_lshl_add_u64 v[30:31], v[0:1], 0, s[16:17]
	s_mov_b32 m0, s8
	s_mov_b64 s[16:17], 0x6ce8780
	global_load_lds_dwordx4 v[30:31], off
	v_lshl_add_u64 v[30:31], v[0:1], 0, s[16:17]
	s_mov_b32 m0, s9
	s_mov_b64 s[16:17], 0x6cf8780
	global_load_lds_dwordx4 v[30:31], off
	v_lshl_add_u64 v[30:31], v[0:1], 0, s[16:17]
	s_mov_b32 m0, s10
	s_mov_b64 s[16:17], 0x23c8780
	global_load_lds_dwordx4 v[30:31], off
	v_lshl_add_u64 v[30:31], v[2:3], 0, s[16:17]
	s_mov_b32 m0, s11
	s_mov_b64 s[16:17], 0x23d8780
	global_load_lds_dwordx4 v[30:31], off
	v_lshl_add_u64 v[30:31], v[2:3], 0, s[16:17]
	s_mov_b32 m0, s12
	s_nop 0
	global_load_lds_dwordx4 v[30:31], off
	ds_read_b128 v[50:53], v4
	ds_read_b128 v[54:57], v4 offset:2048
	ds_read_b128 v[58:61], v4 offset:4096
	ds_read_b128 v[62:65], v4 offset:6144
	ds_read_b128 v[66:69], v5
	ds_read_b128 v[70:73], v5 offset:2048
	ds_read_b128 v[74:77], v6
	ds_read_b128 v[78:81], v6 offset:2048
	ds_read_b128 v[82:85], v6 offset:4096
	ds_read_b128 v[86:89], v6 offset:6144
	ds_read_b128 v[90:93], v7
	ds_read_b128 v[94:97], v7 offset:2048
	s_waitcnt lgkmcnt(0)
	s_setprio 1
	v_mfma_f32_16x16x32_bf16 v[34:37], v[50:53], v[66:69], v[34:37]
	v_mfma_f32_16x16x32_bf16 v[14:17], v[54:57], v[70:73], v[14:17]
	v_mfma_f32_16x16x32_bf16 v[18:21], v[58:61], v[70:73], v[18:21]
	v_mfma_f32_16x16x32_bf16 v[26:29], v[62:65], v[66:69], v[26:29]
	v_mfma_f32_16x16x32_bf16 v[22:25], v[62:65], v[70:73], v[22:25]
	v_mfma_f32_16x16x32_bf16 v[38:41], v[50:53], v[70:73], v[38:41]
	v_mfma_f32_16x16x32_bf16 v[46:49], v[54:57], v[66:69], v[46:49]
	v_mfma_f32_16x16x32_bf16 v[42:45], v[58:61], v[66:69], v[42:45]
	v_mfma_f32_16x16x32_bf16 v[34:37], v[74:77], v[90:93], v[34:37]
	v_mfma_f32_16x16x32_bf16 v[14:17], v[78:81], v[94:97], v[14:17]
	v_mfma_f32_16x16x32_bf16 v[18:21], v[82:85], v[94:97], v[18:21]
	v_mfma_f32_16x16x32_bf16 v[26:29], v[86:89], v[90:93], v[26:29]
	v_mfma_f32_16x16x32_bf16 v[22:25], v[86:89], v[94:97], v[22:25]
	v_mfma_f32_16x16x32_bf16 v[38:41], v[74:77], v[94:97], v[38:41]
	v_mfma_f32_16x16x32_bf16 v[46:49], v[78:81], v[90:93], v[46:49]
	v_mfma_f32_16x16x32_bf16 v[42:45], v[82:85], v[90:93], v[42:45]
	s_setprio 0
	s_mov_b64 s[16:17], 0x6cc8800
	s_mov_b32 m0, s14
	v_lshl_add_u64 v[30:31], v[0:1], 0, s[16:17]
	s_mov_b64 s[16:17], 0x6cd8800
	s_waitcnt vmcnt(0)
	s_barrier
;     ...
;   for (int kt = 0; kt < nk; ++kt) {
;     asm volatile("s_waitcnt vmcnt(0)" ::: "memory");
;     __builtin_amdgcn_s_barrier();
;     if (kt + 1 < nk) stage(kt + 1, (kt + 1) & 1);
;     else if (chained && nbrow >= 0) {
;       const bfr* na = (nA ? nA : A) + (long)(nbrow + r0) * lda + cg;
;       const bfr* nb = (nBt ? nBt : Bt) + (long)(nbcol + r0) * ldb + cg;
; #pragma unroll
;       for (int i = 0; i < 4; ++i)
;         __builtin_amdgcn_global_load_lds((const unsigned*)(na + i * a32), (unsigned*)(smem + tid * 16 + i * 4096), 16, 0, 0);
; #pragma unroll
;       for (int i = 0; i < NF; ++i)
;         __builtin_amdgcn_global_load_lds((const unsigned*)(nb + i * b32), (unsigned*)(smem + 16384 + tid * 16 + i * 4096), 16, 0, 0);
;     }
;     const unsigned bo = (kt & 1) * 32768;
;     bf16x8 af[2][4], bfg[2][4];
;     if (NF == 4) {
;       asm volatile(
;           "ds_read_b128 %0, %16\n\tds_read_b128 %1, %16 offset:2048\n\tds_read_b128 %2, %16 offset:4096\n\tds_read_b128 %3, %16 offset:6144\n\t"
;           "ds_read_b128 %4, %17\n\tds_read_b128 %5, %17 offset:2048\n\tds_read_b128 %6, %17 offset:4096\n\tds_read_b128 %7, %17 offset:6144\n\t"
;           "ds_read_b128 %8, %18\n\tds_read_b128 %9, %18 offset:2048\n\tds_read_b128 %10, %18 offset:4096\n\tds_read_b128 %11, %18 offset:6144\n\t"
;           "ds_read_b128 %12, %19\n\tds_read_b128 %13, %19 offset:2048\n\tds_read_b128 %14, %19 offset:4096\n\tds_read_b128 %15, %19 offset:6144\n\t"
;           "s_waitcnt lgkmcnt(0)"
;           : "=&v"(af[0][0]), "=&v"(af[0][1]), "=&v"(af[0][2]), "=&v"(af[0][3]), "=&v"(bfg[0][0]), "=&v"(bfg[0][1]), "=&v"(bfg[0][2]), "=&v"(bfg[0][3]),
;             "=&v"(af[1][0]), "=&v"(af[1][1]), "=&v"(af[1][2]), "=&v"(af[1][3]), "=&v"(bfg[1][0]), "=&v"(bfg[1][1]), "=&v"(bfg[1][2]), "=&v"(bfg[1][3])
;           : "v"(arow + sw0 + bo), "v"(brw + sw0 + bo), "v"(arow + sw1 + bo), "v"(brw + sw1 + bo)
;           : "memory");
;     } else {
;       asm volatile(
;           "ds_read_b128 %0, %12\n\tds_read_b128 %1, %12 offset:2048\n\tds_read_b128 %2, %12 offset:4096\n\tds_read_b128 %3, %12 offset:6144\n\t"
;           "ds_read_b128 %4, %13\n\tds_read_b128 %5, %13 offset:2048\n\t"
;           "ds_read_b128 %6, %14\n\tds_read_b128 %7, %14 offset:2048\n\tds_read_b128 %8, %14 offset:4096\n\tds_read_b128 %9, %14 offset:6144\n\t"
	global_load_lds_dwordx4 v[30:31], off
	v_lshl_add_u64 v[30:31], v[0:1], 0, s[16:17]
	s_mov_b32 m0, s3
	s_mov_b64 s[16:17], 0x6ce8800
	global_load_lds_dwordx4 v[30:31], off
	v_lshl_add_u64 v[30:31], v[0:1], 0, s[16:17]
	s_mov_b32 m0, s4
	s_mov_b64 s[16:17], 0x6cf8800
	global_load_lds_dwordx4 v[30:31], off
	v_lshl_add_u64 v[30:31], v[0:1], 0, s[16:17]
	s_mov_b32 m0, s6
	s_mov_b64 s[16:17], 0x23c8800
	global_load_lds_dwordx4 v[30:31], off
	v_lshl_add_u64 v[30:31], v[2:3], 0, s[16:17]
	s_mov_b32 m0, s5
	s_mov_b64 s[16:17], 0x23d8800
	global_load_lds_dwordx4 v[30:31], off
	v_lshl_add_u64 v[30:31], v[2:3], 0, s[16:17]
	s_mov_b32 m0, s7
	s_nop 0
	global_load_lds_dwordx4 v[30:31], off
	ds_read_b128 v[50:53], v9
	ds_read_b128 v[54:57], v9 offset:2048
	ds_read_b128 v[58:61], v9 offset:4096
	ds_read_b128 v[62:65], v9 offset:6144
	ds_read_b128 v[66:69], v10
	ds_read_b128 v[70:73], v10 offset:2048
	ds_read_b128 v[74:77], v11
	ds_read_b128 v[78:81], v11 offset:2048
	ds_read_b128 v[82:85], v11 offset:4096
	ds_read_b128 v[86:89], v11 offset:6144
	ds_read_b128 v[90:93], v12
	ds_read_b128 v[94:97], v12 offset:2048
	s_waitcnt lgkmcnt(0)
	s_setprio 1
	v_mfma_f32_16x16x32_bf16 v[34:37], v[50:53], v[66:69], v[34:37]
	v_mfma_f32_16x16x32_bf16 v[14:17], v[54:57], v[70:73], v[14:17]
	v_mfma_f32_16x16x32_bf16 v[18:21], v[58:61], v[70:73], v[18:21]
	v_mfma_f32_16x16x32_bf16 v[26:29], v[62:65], v[66:69], v[26:29]
	v_mfma_f32_16x16x32_bf16 v[22:25], v[62:65], v[70:73], v[22:25]
	v_mfma_f32_16x16x32_bf16 v[38:41], v[50:53], v[70:73], v[38:41]
	v_mfma_f32_16x16x32_bf16 v[46:49], v[54:57], v[66:69], v[46:49]
	v_mfma_f32_16x16x32_bf16 v[42:45], v[58:61], v[66:69], v[42:45]
	v_mfma_f32_16x16x32_bf16 v[34:37], v[74:77], v[90:93], v[34:37]
	v_mfma_f32_16x16x32_bf16 v[14:17], v[78:81], v[94:97], v[14:17]
	v_mfma_f32_16x16x32_bf16 v[18:21], v[82:85], v[94:97], v[18:21]
	v_mfma_f32_16x16x32_bf16 v[26:29], v[86:89], v[90:93], v[26:29]
	v_mfma_f32_16x16x32_bf16 v[22:25], v[86:89], v[94:97], v[22:25]
	v_mfma_f32_16x16x32_bf16 v[38:41], v[74:77], v[94:97], v[38:41]
	v_mfma_f32_16x16x32_bf16 v[46:49], v[78:81], v[90:93], v[46:49]
	v_mfma_f32_16x16x32_bf16 v[42:45], v[82:85], v[90:93], v[42:45]
	s_setprio 0
	s_mov_b64 s[16:17], 0x6cc8880
	s_mov_b32 m0, s13
	v_lshl_add_u64 v[30:31], v[0:1], 0, s[16:17]
	s_mov_b64 s[16:17], 0x6cd8880
	s_waitcnt vmcnt(0)
	s_barrier
	global_load_lds_dwordx4 v[30:31], off
	v_lshl_add_u64 v[30:31], v[0:1], 0, s[16:17]
	s_mov_b32 m0, s8
	s_mov_b64 s[16:17], 0x6ce8880
	global_load_lds_dwordx4 v[30:31], off
	v_lshl_add_u64 v[30:31], v[0:1], 0, s[16:17]
	s_mov_b32 m0, s9
	s_mov_b64 s[16:17], 0x6cf8880
	global_load_lds_dwordx4 v[30:31], off
	v_lshl_add_u64 v[30:31], v[0:1], 0, s[16:17]
	s_mov_b32 m0, s10
	s_mov_b64 s[16:17], 0x23c8880
	global_load_lds_dwordx4 v[30:31], off
	v_lshl_add_u64 v[30:31], v[2:3], 0, s[16:17]
	s_mov_b32 m0, s11
	s_mov_b64 s[16:17], 0x23d8880
	global_load_lds_dwordx4 v[30:31], off
	v_lshl_add_u64 v[30:31], v[2:3], 0, s[16:17]
	s_mov_b32 m0, s12
	s_nop 0
	global_load_lds_dwordx4 v[30:31], off
	ds_read_b128 v[50:53], v4
	ds_read_b128 v[54:57], v4 offset:2048
	ds_read_b128 v[58:61], v4 offset:4096
	ds_read_b128 v[62:65], v4 offset:6144
	ds_read_b128 v[66:69], v5
	ds_read_b128 v[70:73], v5 offset:2048
	ds_read_b128 v[74:77], v6
	ds_read_b128 v[78:81], v6 offset:2048
	ds_read_b128 v[82:85], v6 offset:4096
	ds_read_b128 v[86:89], v6 offset:6144
	ds_read_b128 v[90:93], v7
	ds_read_b128 v[94:97], v7 offset:2048
	s_waitcnt lgkmcnt(0)
	s_setprio 1
	v_mfma_f32_16x16x32_bf16 v[34:37], v[50:53], v[66:69], v[34:37]
	v_mfma_f32_16x16x32_bf16 v[14:17], v[54:57], v[70:73], v[14:17]
	v_mfma_f32_16x16x32_bf16 v[18:21], v[58:61], v[70:73], v[18:21]
	v_mfma_f32_16x16x32_bf16 v[26:29], v[62:65], v[66:69], v[26:29]
	v_mfma_f32_16x16x32_bf16 v[22:25], v[62:65], v[70:73], v[22:25]
	v_mfma_f32_16x16x32_bf16 v[38:41], v[50:53], v[70:73], v[38:41]
	v_mfma_f32_16x16x32_bf16 v[46:49], v[54:57], v[66:69], v[46:49]
	v_mfma_f32_16x16x32_bf16 v[42:45], v[58:61], v[66:69], v[42:45]
	v_mfma_f32_16x16x32_bf16 v[34:37], v[74:77], v[90:93], v[34:37]
	v_mfma_f32_16x16x32_bf16 v[14:17], v[78:81], v[94:97], v[14:17]
	v_mfma_f32_16x16x32_bf16 v[18:21], v[82:85], v[94:97], v[18:21]
	v_mfma_f32_16x16x32_bf16 v[26:29], v[86:89], v[90:93], v[26:29]
	v_mfma_f32_16x16x32_bf16 v[22:25], v[86:89], v[94:97], v[22:25]
	v_mfma_f32_16x16x32_bf16 v[38:41], v[74:77], v[94:97], v[38:41]
	v_mfma_f32_16x16x32_bf16 v[46:49], v[78:81], v[90:93], v[46:49]
	v_mfma_f32_16x16x32_bf16 v[42:45], v[82:85], v[90:93], v[42:45]
	s_setprio 0
	s_mov_b32 m0, s14
	s_mov_b64 s[14:15], 0x6cc8900
	v_lshl_add_u64 v[30:31], v[0:1], 0, s[14:15]
	s_mov_b64 s[14:15], 0x6cd8900
	s_waitcnt vmcnt(0)
	s_barrier
;     ...
;   for (int kt = 0; kt < nk; ++kt) {
;     asm volatile("s_waitcnt vmcnt(0)" ::: "memory");
;     __builtin_amdgcn_s_barrier();
;     if (kt + 1 < nk) stage(kt + 1, (kt + 1) & 1);
;     else if (chained && nbrow >= 0) {
;       const bfr* na = (nA ? nA : A) + (long)(nbrow + r0) * lda + cg;
;       const bfr* nb = (nBt ? nBt : Bt) + (long)(nbcol + r0) * ldb + cg;
; #pragma unroll
;       for (int i = 0; i < 4; ++i)
;         __builtin_amdgcn_global_load_lds((const unsigned*)(na + i * a32), (unsigned*)(smem + tid * 16 + i * 4096), 16, 0, 0);
; #pragma unroll
;       for (int i = 0; i < NF; ++i)
;         __builtin_amdgcn_global_load_lds((const unsigned*)(nb + i * b32), (unsigned*)(smem + 16384 + tid * 16 + i * 4096), 16, 0, 0);
;     }
;     const unsigned bo = (kt & 1) * 32768;
;     bf16x8 af[2][4], bfg[2][4];
;     if (NF == 4) {
;       asm volatile(
;           "ds_read_b128 %0, %16\n\tds_read_b128 %1, %16 offset:2048\n\tds_read_b128 %2, %16 offset:4096\n\tds_read_b128 %3, %16 offset:6144\n\t"
;           "ds_read_b128 %4, %17\n\tds_read_b128 %5, %17 offset:2048\n\tds_read_b128 %6, %17 offset:4096\n\tds_read_b128 %7, %17 offset:6144\n\t"
;           "ds_read_b128 %8, %18\n\tds_read_b128 %9, %18 offset:2048\n\tds_read_b128 %10, %18 offset:4096\n\tds_read_b128 %11, %18 offset:6144\n\t"
;           "ds_read_b128 %12, %19\n\tds_read_b128 %13, %19 offset:2048\n\tds_read_b128 %14, %19 offset:4096\n\tds_read_b128 %15, %19 offset:6144\n\t"
;           "s_waitcnt lgkmcnt(0)"
;           : "=&v"(af[0][0]), "=&v"(af[0][1]), "=&v"(af[0][2]), "=&v"(af[0][3]), "=&v"(bfg[0][0]), "=&v"(bfg[0][1]), "=&v"(bfg[0][2]), "=&v"(bfg[0][3]),
;             "=&v"(af[1][0]), "=&v"(af[1][1]), "=&v"(af[1][2]), "=&v"(af[1][3]), "=&v"(bfg[1][0]), "=&v"(bfg[1][1]), "=&v"(bfg[1][2]), "=&v"(bfg[1][3])
;           : "v"(arow + sw0 + bo), "v"(brw + sw0 + bo), "v"(arow + sw1 + bo), "v"(brw + sw1 + bo)
;           : "memory");
;     } else {
;       asm volatile(
;           "ds_read_b128 %0, %12\n\tds_read_b128 %1, %12 offset:2048\n\tds_read_b128 %2, %12 offset:4096\n\tds_read_b128 %3, %12 offset:6144\n\t"
;           "ds_read_b128 %4, %13\n\tds_read_b128 %5, %13 offset:2048\n\t"
;           "ds_read_b128 %6, %14\n\tds_read_b128 %7, %14 offset:2048\n\tds_read_b128 %8, %14 offset:4096\n\tds_read_b128 %9, %14 offset:6144\n\t"
	global_load_lds_dwordx4 v[30:31], off
	v_lshl_add_u64 v[30:31], v[0:1], 0, s[14:15]
	s_mov_b32 m0, s3
	s_mov_b64 s[14:15], 0x6ce8900
	global_load_lds_dwordx4 v[30:31], off
	v_lshl_add_u64 v[30:31], v[0:1], 0, s[14:15]
	s_mov_b32 m0, s4
	s_mov_b64 s[14:15], 0x6cf8900
	global_load_lds_dwordx4 v[30:31], off
	v_lshl_add_u64 v[30:31], v[0:1], 0, s[14:15]
	s_mov_b32 m0, s6
	s_mov_b64 s[14:15], 0x23c8900
	global_load_lds_dwordx4 v[30:31], off
	v_lshl_add_u64 v[30:31], v[2:3], 0, s[14:15]
	s_mov_b32 m0, s5
	s_mov_b64 s[14:15], 0x23d8900
	global_load_lds_dwordx4 v[30:31], off
	v_lshl_add_u64 v[30:31], v[2:3], 0, s[14:15]
	s_mov_b32 m0, s7
	s_nop 0
	global_load_lds_dwordx4 v[30:31], off
	ds_read_b128 v[50:53], v9
	ds_read_b128 v[54:57], v9 offset:2048
	ds_read_b128 v[58:61], v9 offset:4096
	ds_read_b128 v[62:65], v9 offset:6144
	ds_read_b128 v[66:69], v10
	ds_read_b128 v[70:73], v10 offset:2048
	ds_read_b128 v[74:77], v11
	ds_read_b128 v[78:81], v11 offset:2048
	ds_read_b128 v[82:85], v11 offset:4096
	ds_read_b128 v[86:89], v11 offset:6144
	ds_read_b128 v[90:93], v12
	ds_read_b128 v[94:97], v12 offset:2048
	s_waitcnt lgkmcnt(0)
	s_setprio 1
	v_mfma_f32_16x16x32_bf16 v[34:37], v[50:53], v[66:69], v[34:37]
	v_mfma_f32_16x16x32_bf16 v[14:17], v[54:57], v[70:73], v[14:17]
	v_mfma_f32_16x16x32_bf16 v[18:21], v[58:61], v[70:73], v[18:21]
	v_mfma_f32_16x16x32_bf16 v[26:29], v[62:65], v[66:69], v[26:29]
	v_mfma_f32_16x16x32_bf16 v[22:25], v[62:65], v[70:73], v[22:25]
	v_mfma_f32_16x16x32_bf16 v[38:41], v[50:53], v[70:73], v[38:41]
	v_mfma_f32_16x16x32_bf16 v[46:49], v[54:57], v[66:69], v[46:49]
	v_mfma_f32_16x16x32_bf16 v[42:45], v[58:61], v[66:69], v[42:45]
	v_mfma_f32_16x16x32_bf16 v[34:37], v[74:77], v[90:93], v[34:37]
	v_mfma_f32_16x16x32_bf16 v[14:17], v[78:81], v[94:97], v[14:17]
	v_mfma_f32_16x16x32_bf16 v[18:21], v[82:85], v[94:97], v[18:21]
	v_mfma_f32_16x16x32_bf16 v[26:29], v[86:89], v[90:93], v[26:29]
	v_mfma_f32_16x16x32_bf16 v[22:25], v[86:89], v[94:97], v[22:25]
	v_mfma_f32_16x16x32_bf16 v[38:41], v[74:77], v[94:97], v[38:41]
	v_mfma_f32_16x16x32_bf16 v[46:49], v[78:81], v[90:93], v[46:49]
	v_mfma_f32_16x16x32_bf16 v[42:45], v[82:85], v[90:93], v[42:45]
	s_setprio 0
	s_mov_b64 s[14:15], 0x6cc8980
	s_mov_b32 m0, s13
	v_lshl_add_u64 v[30:31], v[0:1], 0, s[14:15]
	s_mov_b64 s[14:15], 0x6cd8980
	s_waitcnt vmcnt(0)
	s_barrier
	global_load_lds_dwordx4 v[30:31], off
	v_lshl_add_u64 v[30:31], v[0:1], 0, s[14:15]
	s_mov_b32 m0, s8
	s_mov_b64 s[14:15], 0x6ce8980
	global_load_lds_dwordx4 v[30:31], off
	v_lshl_add_u64 v[30:31], v[0:1], 0, s[14:15]
	s_mov_b32 m0, s9
	s_mov_b64 s[14:15], 0x6cf8980
	global_load_lds_dwordx4 v[30:31], off
	v_lshl_add_u64 v[30:31], v[0:1], 0, s[14:15]
	s_mov_b32 m0, s10
	s_mov_b64 s[14:15], 0x23c8980
	global_load_lds_dwordx4 v[30:31], off
	v_lshl_add_u64 v[30:31], v[2:3], 0, s[14:15]
	s_mov_b32 m0, s11
	s_mov_b64 s[14:15], 0x23d8980
	global_load_lds_dwordx4 v[30:31], off
	v_lshl_add_u64 v[30:31], v[2:3], 0, s[14:15]
	s_mov_b32 m0, s12
	s_nop 0
	global_load_lds_dwordx4 v[30:31], off
	ds_read_b128 v[50:53], v4
	ds_read_b128 v[54:57], v4 offset:2048
	ds_read_b128 v[58:61], v4 offset:4096
	ds_read_b128 v[62:65], v4 offset:6144
	ds_read_b128 v[66:69], v5
	ds_read_b128 v[70:73], v5 offset:2048
	ds_read_b128 v[74:77], v6
	ds_read_b128 v[78:81], v6 offset:2048
	ds_read_b128 v[82:85], v6 offset:4096
	ds_read_b128 v[86:89], v6 offset:6144
	ds_read_b128 v[90:93], v7
	ds_read_b128 v[94:97], v7 offset:2048
	s_waitcnt lgkmcnt(0)
	s_setprio 1
	v_mfma_f32_16x16x32_bf16 v[34:37], v[50:53], v[66:69], v[34:37]
	v_mfma_f32_16x16x32_bf16 v[14:17], v[54:57], v[70:73], v[14:17]
	v_mfma_f32_16x16x32_bf16 v[18:21], v[58:61], v[70:73], v[18:21]
	v_mfma_f32_16x16x32_bf16 v[26:29], v[62:65], v[66:69], v[26:29]
	v_mfma_f32_16x16x32_bf16 v[22:25], v[62:65], v[70:73], v[22:25]
	v_mfma_f32_16x16x32_bf16 v[38:41], v[50:53], v[70:73], v[38:41]
	v_mfma_f32_16x16x32_bf16 v[46:49], v[54:57], v[66:69], v[46:49]
	v_mfma_f32_16x16x32_bf16 v[42:45], v[58:61], v[66:69], v[42:45]
	v_mfma_f32_16x16x32_bf16 v[34:37], v[74:77], v[90:93], v[34:37]
	v_mfma_f32_16x16x32_bf16 v[14:17], v[78:81], v[94:97], v[14:17]
	v_mfma_f32_16x16x32_bf16 v[18:21], v[82:85], v[94:97], v[18:21]
	v_mfma_f32_16x16x32_bf16 v[26:29], v[86:89], v[90:93], v[26:29]
	v_mfma_f32_16x16x32_bf16 v[22:25], v[86:89], v[94:97], v[22:25]
	v_mfma_f32_16x16x32_bf16 v[38:41], v[74:77], v[94:97], v[38:41]
	v_mfma_f32_16x16x32_bf16 v[46:49], v[78:81], v[90:93], v[46:49]
	v_mfma_f32_16x16x32_bf16 v[42:45], v[82:85], v[90:93], v[42:45]
	s_setprio 0
	s_mov_b64 s[14:15], 0x6cc8a00
	v_readfirstlane_b32 s16, v8
	v_lshl_add_u64 v[30:31], v[0:1], 0, s[14:15]
	s_mov_b32 m0, s16
	s_mov_b64 s[14:15], 0x6cd8a00
	s_waitcnt vmcnt(0)
	s_barrier
;     ...
;   for (int kt = 0; kt < nk; ++kt) {
;     asm volatile("s_waitcnt vmcnt(0)" ::: "memory");
;     __builtin_amdgcn_s_barrier();
;     if (kt + 1 < nk) stage(kt + 1, (kt + 1) & 1);
;     else if (chained && nbrow >= 0) {
;       const bfr* na = (nA ? nA : A) + (long)(nbrow + r0) * lda + cg;
;       const bfr* nb = (nBt ? nBt : Bt) + (long)(nbcol + r0) * ldb + cg;
; #pragma unroll
;       for (int i = 0; i < 4; ++i)
;         __builtin_amdgcn_global_load_lds((const unsigned*)(na + i * a32), (unsigned*)(smem + tid * 16 + i * 4096), 16, 0, 0);
; #pragma unroll
;       for (int i = 0; i < NF; ++i)
;         __builtin_amdgcn_global_load_lds((const unsigned*)(nb + i * b32), (unsigned*)(smem + 16384 + tid * 16 + i * 4096), 16, 0, 0);
;     }
;     const unsigned bo = (kt & 1) * 32768;
;     bf16x8 af[2][4], bfg[2][4];
;     if (NF == 4) {
;       asm volatile(
;           "ds_read_b128 %0, %16\n\tds_read_b128 %1, %16 offset:2048\n\tds_read_b128 %2, %16 offset:4096\n\tds_read_b128 %3, %16 offset:6144\n\t"
;           "ds_read_b128 %4, %17\n\tds_read_b128 %5, %17 offset:2048\n\tds_read_b128 %6, %17 offset:4096\n\tds_read_b128 %7, %17 offset:6144\n\t"
;           "ds_read_b128 %8, %18\n\tds_read_b128 %9, %18 offset:2048\n\tds_read_b128 %10, %18 offset:4096\n\tds_read_b128 %11, %18 offset:6144\n\t"
;           "ds_read_b128 %12, %19\n\tds_read_b128 %13, %19 offset:2048\n\tds_read_b128 %14, %19 offset:4096\n\tds_read_b128 %15, %19 offset:6144\n\t"
;           "s_waitcnt lgkmcnt(0)"
;           : "=&v"(af[0][0]), "=&v"(af[0][1]), "=&v"(af[0][2]), "=&v"(af[0][3]), "=&v"(bfg[0][0]), "=&v"(bfg[0][1]), "=&v"(bfg[0][2]), "=&v"(bfg[0][3]),
;             "=&v"(af[1][0]), "=&v"(af[1][1]), "=&v"(af[1][2]), "=&v"(af[1][3]), "=&v"(bfg[1][0]), "=&v"(bfg[1][1]), "=&v"(bfg[1][2]), "=&v"(bfg[1][3])
;           : "v"(arow + sw0 + bo), "v"(brw + sw0 + bo), "v"(arow + sw1 + bo), "v"(brw + sw1 + bo)
;           : "memory");
;     } else {
;       asm volatile(
;           "ds_read_b128 %0, %12\n\tds_read_b128 %1, %12 offset:2048\n\tds_read_b128 %2, %12 offset:4096\n\tds_read_b128 %3, %12 offset:6144\n\t"
;           "ds_read_b128 %4, %13\n\tds_read_b128 %5, %13 offset:2048\n\t"
;           "ds_read_b128 %6, %14\n\tds_read_b128 %7, %14 offset:2048\n\tds_read_b128 %8, %14 offset:4096\n\tds_read_b128 %9, %14 offset:6144\n\t"
	global_load_lds_dwordx4 v[30:31], off
	v_lshl_add_u64 v[30:31], v[0:1], 0, s[14:15]
	s_mov_b32 m0, s3
	s_mov_b64 s[14:15], 0x6ce8a00
	global_load_lds_dwordx4 v[30:31], off
	v_lshl_add_u64 v[30:31], v[0:1], 0, s[14:15]
	s_mov_b32 m0, s4
	s_mov_b64 s[14:15], 0x6cf8a00
	global_load_lds_dwordx4 v[30:31], off
	v_lshl_add_u64 v[30:31], v[0:1], 0, s[14:15]
	s_mov_b32 m0, s6
	s_mov_b64 s[14:15], 0x23c8a00
	global_load_lds_dwordx4 v[30:31], off
	v_lshl_add_u64 v[30:31], v[2:3], 0, s[14:15]
	s_mov_b32 m0, s5
	s_mov_b64 s[14:15], 0x23d8a00
	global_load_lds_dwordx4 v[30:31], off
	v_lshl_add_u64 v[30:31], v[2:3], 0, s[14:15]
	s_mov_b32 m0, s7
	s_nop 0
	global_load_lds_dwordx4 v[30:31], off
	ds_read_b128 v[50:53], v9
	ds_read_b128 v[54:57], v9 offset:2048
	ds_read_b128 v[58:61], v9 offset:4096
	ds_read_b128 v[62:65], v9 offset:6144
	ds_read_b128 v[66:69], v10
	ds_read_b128 v[70:73], v10 offset:2048
	ds_read_b128 v[74:77], v11
	ds_read_b128 v[78:81], v11 offset:2048
	ds_read_b128 v[82:85], v11 offset:4096
	ds_read_b128 v[86:89], v11 offset:6144
	ds_read_b128 v[90:93], v12
	ds_read_b128 v[94:97], v12 offset:2048
	s_waitcnt lgkmcnt(0)
	s_setprio 1
	v_mfma_f32_16x16x32_bf16 v[34:37], v[50:53], v[66:69], v[34:37]
	v_mfma_f32_16x16x32_bf16 v[14:17], v[54:57], v[70:73], v[14:17]
	v_mfma_f32_16x16x32_bf16 v[18:21], v[58:61], v[70:73], v[18:21]
	v_mfma_f32_16x16x32_bf16 v[26:29], v[62:65], v[66:69], v[26:29]
	v_mfma_f32_16x16x32_bf16 v[22:25], v[62:65], v[70:73], v[22:25]
	v_mfma_f32_16x16x32_bf16 v[38:41], v[50:53], v[70:73], v[38:41]
	v_mfma_f32_16x16x32_bf16 v[46:49], v[54:57], v[66:69], v[46:49]
	v_mfma_f32_16x16x32_bf16 v[42:45], v[58:61], v[66:69], v[42:45]
	v_mfma_f32_16x16x32_bf16 v[34:37], v[74:77], v[90:93], v[34:37]
	v_mfma_f32_16x16x32_bf16 v[14:17], v[78:81], v[94:97], v[14:17]
	v_mfma_f32_16x16x32_bf16 v[18:21], v[82:85], v[94:97], v[18:21]
	v_mfma_f32_16x16x32_bf16 v[26:29], v[86:89], v[90:93], v[26:29]
	v_mfma_f32_16x16x32_bf16 v[22:25], v[86:89], v[94:97], v[22:25]
	v_mfma_f32_16x16x32_bf16 v[38:41], v[74:77], v[94:97], v[38:41]
	v_mfma_f32_16x16x32_bf16 v[46:49], v[78:81], v[90:93], v[46:49]
	v_mfma_f32_16x16x32_bf16 v[42:45], v[82:85], v[90:93], v[42:45]
	s_setprio 0
	s_mov_b64 s[14:15], 0x6cc8a80
	s_mov_b32 m0, s13
	v_lshl_add_u64 v[30:31], v[0:1], 0, s[14:15]
	s_mov_b64 s[14:15], 0x6cd8a80
	s_waitcnt vmcnt(0)
	s_barrier
	global_load_lds_dwordx4 v[30:31], off
	v_lshl_add_u64 v[30:31], v[0:1], 0, s[14:15]
	s_mov_b32 m0, s8
	s_mov_b64 s[14:15], 0x6ce8a80
	global_load_lds_dwordx4 v[30:31], off
	v_lshl_add_u64 v[30:31], v[0:1], 0, s[14:15]
	s_mov_b32 m0, s9
	s_mov_b64 s[14:15], 0x6cf8a80
	global_load_lds_dwordx4 v[30:31], off
	v_lshl_add_u64 v[30:31], v[0:1], 0, s[14:15]
	s_mov_b32 m0, s10
	s_mov_b64 s[14:15], 0x23c8a80
	global_load_lds_dwordx4 v[30:31], off
	v_lshl_add_u64 v[30:31], v[2:3], 0, s[14:15]
	s_mov_b32 m0, s11
	s_mov_b64 s[14:15], 0x23d8a80
	global_load_lds_dwordx4 v[30:31], off
	v_lshl_add_u64 v[30:31], v[2:3], 0, s[14:15]
	s_mov_b32 m0, s12
	s_nop 0
	global_load_lds_dwordx4 v[30:31], off
	ds_read_b128 v[50:53], v4
	ds_read_b128 v[54:57], v4 offset:2048
	ds_read_b128 v[58:61], v4 offset:4096
	ds_read_b128 v[62:65], v4 offset:6144
	ds_read_b128 v[66:69], v5
	ds_read_b128 v[70:73], v5 offset:2048
	ds_read_b128 v[74:77], v6
	ds_read_b128 v[78:81], v6 offset:2048
	ds_read_b128 v[82:85], v6 offset:4096
	ds_read_b128 v[86:89], v6 offset:6144
	ds_read_b128 v[90:93], v7
	ds_read_b128 v[94:97], v7 offset:2048
	s_waitcnt lgkmcnt(0)
	s_setprio 1
	v_mfma_f32_16x16x32_bf16 v[34:37], v[50:53], v[66:69], v[34:37]
	v_mfma_f32_16x16x32_bf16 v[14:17], v[54:57], v[70:73], v[14:17]
	v_mfma_f32_16x16x32_bf16 v[18:21], v[58:61], v[70:73], v[18:21]
	v_mfma_f32_16x16x32_bf16 v[26:29], v[62:65], v[66:69], v[26:29]
	v_mfma_f32_16x16x32_bf16 v[22:25], v[62:65], v[70:73], v[22:25]
	v_mfma_f32_16x16x32_bf16 v[38:41], v[50:53], v[70:73], v[38:41]
	v_mfma_f32_16x16x32_bf16 v[46:49], v[54:57], v[66:69], v[46:49]
	v_mfma_f32_16x16x32_bf16 v[42:45], v[58:61], v[66:69], v[42:45]
	v_mfma_f32_16x16x32_bf16 v[34:37], v[74:77], v[90:93], v[34:37]
	v_mfma_f32_16x16x32_bf16 v[14:17], v[78:81], v[94:97], v[14:17]
	v_mfma_f32_16x16x32_bf16 v[18:21], v[82:85], v[94:97], v[18:21]
	v_mfma_f32_16x16x32_bf16 v[26:29], v[86:89], v[90:93], v[26:29]
	v_mfma_f32_16x16x32_bf16 v[22:25], v[86:89], v[94:97], v[22:25]
	v_mfma_f32_16x16x32_bf16 v[38:41], v[74:77], v[94:97], v[38:41]
	v_mfma_f32_16x16x32_bf16 v[46:49], v[78:81], v[90:93], v[46:49]
	v_mfma_f32_16x16x32_bf16 v[42:45], v[82:85], v[90:93], v[42:45]
	s_setprio 0
	s_mov_b64 s[14:15], 0x6cc8b00
	s_mov_b32 m0, s16
	v_lshl_add_u64 v[30:31], v[0:1], 0, s[14:15]
	s_mov_b64 s[14:15], 0x6cd8b00
	s_waitcnt vmcnt(0)
	s_barrier
;     ...
;   for (int kt = 0; kt < nk; ++kt) {
;     asm volatile("s_waitcnt vmcnt(0)" ::: "memory");
;     __builtin_amdgcn_s_barrier();
;     if (kt + 1 < nk) stage(kt + 1, (kt + 1) & 1);
;     else if (chained && nbrow >= 0) {
;       const bfr* na = (nA ? nA : A) + (long)(nbrow + r0) * lda + cg;
;       const bfr* nb = (nBt ? nBt : Bt) + (long)(nbcol + r0) * ldb + cg;
; #pragma unroll
;       for (int i = 0; i < 4; ++i)
;         __builtin_amdgcn_global_load_lds((const unsigned*)(na + i * a32), (unsigned*)(smem + tid * 16 + i * 4096), 16, 0, 0);
; #pragma unroll
;       for (int i = 0; i < NF; ++i)
;         __builtin_amdgcn_global_load_lds((const unsigned*)(nb + i * b32), (unsigned*)(smem + 16384 + tid * 16 + i * 4096), 16, 0, 0);
;     }
;     const unsigned bo = (kt & 1) * 32768;
;     bf16x8 af[2][4], bfg[2][4];
;     if (NF == 4) {
;       asm volatile(
;           "ds_read_b128 %0, %16\n\tds_read_b128 %1, %16 offset:2048\n\tds_read_b128 %2, %16 offset:4096\n\tds_read_b128 %3, %16 offset:6144\n\t"
;           "ds_read_b128 %4, %17\n\tds_read_b128 %5, %17 offset:2048\n\tds_read_b128 %6, %17 offset:4096\n\tds_read_b128 %7, %17 offset:6144\n\t"
;           "ds_read_b128 %8, %18\n\tds_read_b128 %9, %18 offset:2048\n\tds_read_b128 %10, %18 offset:4096\n\tds_read_b128 %11, %18 offset:6144\n\t"
;           "ds_read_b128 %12, %19\n\tds_read_b128 %13, %19 offset:2048\n\tds_read_b128 %14, %19 offset:4096\n\tds_read_b128 %15, %19 offset:6144\n\t"
;           "s_waitcnt lgkmcnt(0)"
;           : "=&v"(af[0][0]), "=&v"(af[0][1]), "=&v"(af[0][2]), "=&v"(af[0][3]), "=&v"(bfg[0][0]), "=&v"(bfg[0][1]), "=&v"(bfg[0][2]), "=&v"(bfg[0][3]),
;             "=&v"(af[1][0]), "=&v"(af[1][1]), "=&v"(af[1][2]), "=&v"(af[1][3]), "=&v"(bfg[1][0]), "=&v"(bfg[1][1]), "=&v"(bfg[1][2]), "=&v"(bfg[1][3])
;           : "v"(arow + sw0 + bo), "v"(brw + sw0 + bo), "v"(arow + sw1 + bo), "v"(brw + sw1 + bo)
;           : "memory");
;     } else {
;       asm volatile(
;           "ds_read_b128 %0, %12\n\tds_read_b128 %1, %12 offset:2048\n\tds_read_b128 %2, %12 offset:4096\n\tds_read_b128 %3, %12 offset:6144\n\t"
;           "ds_read_b128 %4, %13\n\tds_read_b128 %5, %13 offset:2048\n\t"
;           "ds_read_b128 %6, %14\n\tds_read_b128 %7, %14 offset:2048\n\tds_read_b128 %8, %14 offset:4096\n\tds_read_b128 %9, %14 offset:6144\n\t"
	global_load_lds_dwordx4 v[30:31], off
	v_lshl_add_u64 v[30:31], v[0:1], 0, s[14:15]
	s_mov_b32 m0, s3
	s_mov_b64 s[14:15], 0x6ce8b00
	global_load_lds_dwordx4 v[30:31], off
	v_lshl_add_u64 v[30:31], v[0:1], 0, s[14:15]
	s_mov_b32 m0, s4
	s_mov_b64 s[14:15], 0x6cf8b00
	global_load_lds_dwordx4 v[30:31], off
	v_lshl_add_u64 v[30:31], v[0:1], 0, s[14:15]
	s_mov_b32 m0, s6
	s_mov_b64 s[14:15], 0x23c8b00
	global_load_lds_dwordx4 v[30:31], off
	v_lshl_add_u64 v[30:31], v[2:3], 0, s[14:15]
	s_mov_b32 m0, s5
	s_mov_b64 s[4:5], 0x23d8b00
	global_load_lds_dwordx4 v[30:31], off
	v_lshl_add_u64 v[30:31], v[2:3], 0, s[4:5]
	s_mov_b32 m0, s7
	s_nop 0
	global_load_lds_dwordx4 v[30:31], off
	ds_read_b128 v[50:53], v9
	ds_read_b128 v[54:57], v9 offset:2048
	ds_read_b128 v[58:61], v9 offset:4096
	ds_read_b128 v[62:65], v9 offset:6144
	ds_read_b128 v[66:69], v10
	ds_read_b128 v[70:73], v10 offset:2048
	ds_read_b128 v[74:77], v11
	ds_read_b128 v[78:81], v11 offset:2048
	ds_read_b128 v[82:85], v11 offset:4096
	ds_read_b128 v[86:89], v11 offset:6144
	ds_read_b128 v[90:93], v12
	ds_read_b128 v[94:97], v12 offset:2048
	s_waitcnt lgkmcnt(0)
	s_setprio 1
	v_mfma_f32_16x16x32_bf16 v[34:37], v[50:53], v[66:69], v[34:37]
	v_mfma_f32_16x16x32_bf16 v[14:17], v[54:57], v[70:73], v[14:17]
	v_mfma_f32_16x16x32_bf16 v[18:21], v[58:61], v[70:73], v[18:21]
	v_mfma_f32_16x16x32_bf16 v[26:29], v[62:65], v[66:69], v[26:29]
	v_mfma_f32_16x16x32_bf16 v[22:25], v[62:65], v[70:73], v[22:25]
	v_mfma_f32_16x16x32_bf16 v[38:41], v[50:53], v[70:73], v[38:41]
	v_mfma_f32_16x16x32_bf16 v[46:49], v[54:57], v[66:69], v[46:49]
	v_mfma_f32_16x16x32_bf16 v[42:45], v[58:61], v[66:69], v[42:45]
	v_mfma_f32_16x16x32_bf16 v[34:37], v[74:77], v[90:93], v[34:37]
	v_mfma_f32_16x16x32_bf16 v[14:17], v[78:81], v[94:97], v[14:17]
	v_mfma_f32_16x16x32_bf16 v[18:21], v[82:85], v[94:97], v[18:21]
	v_mfma_f32_16x16x32_bf16 v[26:29], v[86:89], v[90:93], v[26:29]
	v_mfma_f32_16x16x32_bf16 v[22:25], v[86:89], v[94:97], v[22:25]
	v_mfma_f32_16x16x32_bf16 v[38:41], v[74:77], v[94:97], v[38:41]
	v_mfma_f32_16x16x32_bf16 v[46:49], v[78:81], v[90:93], v[46:49]
	v_mfma_f32_16x16x32_bf16 v[42:45], v[82:85], v[90:93], v[42:45]
	s_setprio 0
	s_mov_b64 s[4:5], 0x6cc8b80
	s_mov_b32 m0, s13
	v_lshl_add_u64 v[30:31], v[0:1], 0, s[4:5]
	s_mov_b64 s[4:5], 0x6cd8b80
	s_waitcnt vmcnt(0)
	s_barrier
	global_load_lds_dwordx4 v[30:31], off
	v_lshl_add_u64 v[30:31], v[0:1], 0, s[4:5]
	s_mov_b32 m0, s8
	s_mov_b64 s[4:5], 0x6ce8b80
	global_load_lds_dwordx4 v[30:31], off
	v_lshl_add_u64 v[30:31], v[0:1], 0, s[4:5]
	s_mov_b32 m0, s9
	s_mov_b64 s[4:5], 0x6cf8b80
	global_load_lds_dwordx4 v[30:31], off
	v_lshl_add_u64 v[0:1], v[0:1], 0, s[4:5]
	s_mov_b32 m0, s10
	s_mov_b64 s[4:5], 0x23c8b80
	global_load_lds_dwordx4 v[0:1], off
	v_lshl_add_u64 v[0:1], v[2:3], 0, s[4:5]
	s_mov_b32 m0, s11
	s_mov_b64 s[4:5], 0x23d8b80
	global_load_lds_dwordx4 v[0:1], off
	v_lshl_add_u64 v[0:1], v[2:3], 0, s[4:5]
	s_mov_b32 m0, s12
	s_nop 0
	global_load_lds_dwordx4 v[0:1], off
	ds_read_b128 v[0:3], v4
	ds_read_b128 v[50:53], v4 offset:2048
	ds_read_b128 v[54:57], v4 offset:4096
	ds_read_b128 v[58:61], v4 offset:6144
	ds_read_b128 v[62:65], v5
	ds_read_b128 v[66:69], v5 offset:2048
	ds_read_b128 v[70:73], v6
	ds_read_b128 v[74:77], v6 offset:2048
	ds_read_b128 v[78:81], v6 offset:4096
	ds_read_b128 v[82:85], v6 offset:6144
	ds_read_b128 v[86:89], v7
	ds_read_b128 v[90:93], v7 offset:2048
	s_waitcnt lgkmcnt(0)
	s_setprio 1
	v_mfma_f32_16x16x32_bf16 v[4:7], v[0:3], v[62:65], v[34:37]
	v_mfma_f32_16x16x32_bf16 v[0:3], v[0:3], v[66:69], v[38:41]
	v_mfma_f32_16x16x32_bf16 v[34:37], v[50:53], v[62:65], v[46:49]
	v_mfma_f32_16x16x32_bf16 v[14:17], v[50:53], v[66:69], v[14:17]
	v_mfma_f32_16x16x32_bf16 v[18:21], v[54:57], v[66:69], v[18:21]
	v_mfma_f32_16x16x32_bf16 v[26:29], v[58:61], v[62:65], v[26:29]
	v_mfma_f32_16x16x32_bf16 v[22:25], v[58:61], v[66:69], v[22:25]
	v_mfma_f32_16x16x32_bf16 v[38:41], v[54:57], v[62:65], v[42:45]
	v_mfma_f32_16x16x32_bf16 v[4:7], v[70:73], v[86:89], v[4:7]
	v_mfma_f32_16x16x32_bf16 v[0:3], v[70:73], v[90:93], v[0:3]
	v_mfma_f32_16x16x32_bf16 v[34:37], v[74:77], v[86:89], v[34:37]
	v_mfma_f32_16x16x32_bf16 v[14:17], v[74:77], v[90:93], v[14:17]
	v_mfma_f32_16x16x32_bf16 v[18:21], v[78:81], v[90:93], v[18:21]
	v_mfma_f32_16x16x32_bf16 v[26:29], v[82:85], v[86:89], v[26:29]
	v_mfma_f32_16x16x32_bf16 v[22:25], v[82:85], v[90:93], v[22:25]
	v_mfma_f32_16x16x32_bf16 v[38:41], v[78:81], v[86:89], v[38:41]
	s_setprio 0
	s_waitcnt vmcnt(0)
	s_barrier
;     ...
;   for (int kt = 0; kt < nk; ++kt) {
;     asm volatile("s_waitcnt vmcnt(0)" ::: "memory");
;     __builtin_amdgcn_s_barrier();
;     if (kt + 1 < nk) stage(kt + 1, (kt + 1) & 1);
;     else if (chained && nbrow >= 0) {
;       const bfr* na = (nA ? nA : A) + (long)(nbrow + r0) * lda + cg;
;       const bfr* nb = (nBt ? nBt : Bt) + (long)(nbcol + r0) * ldb + cg;
; #pragma unroll
;       for (int i = 0; i < 4; ++i)
;         __builtin_amdgcn_global_load_lds((const unsigned*)(na + i * a32), (unsigned*)(smem + tid * 16 + i * 4096), 16, 0, 0);
; #pragma unroll
;       for (int i = 0; i < NF; ++i)
;         __builtin_amdgcn_global_load_lds((const unsigned*)(nb + i * b32), (unsigned*)(smem + 16384 + tid * 16 + i * 4096), 16, 0, 0);
;     }
;     const unsigned bo = (kt & 1) * 32768;
;     bf16x8 af[2][4], bfg[2][4];
;     if (NF == 4) {
;       asm volatile(
;           "ds_read_b128 %0, %16\n\tds_read_b128 %1, %16 offset:2048\n\tds_read_b128 %2, %16 offset:4096\n\tds_read_b128 %3, %16 offset:6144\n\t"
;           "ds_read_b128 %4, %17\n\tds_read_b128 %5, %17 offset:2048\n\tds_read_b128 %6, %17 offset:4096\n\tds_read_b128 %7, %17 offset:6144\n\t"
;           "ds_read_b128 %8, %18\n\tds_read_b128 %9, %18 offset:2048\n\tds_read_b128 %10, %18 offset:4096\n\tds_read_b128 %11, %18 offset:6144\n\t"
;           "ds_read_b128 %12, %19\n\tds_read_b128 %13, %19 offset:2048\n\tds_read_b128 %14, %19 offset:4096\n\tds_read_b128 %15, %19 offset:6144\n\t"
;           "s_waitcnt lgkmcnt(0)"
;           : "=&v"(af[0][0]), "=&v"(af[0][1]), "=&v"(af[0][2]), "=&v"(af[0][3]), "=&v"(bfg[0][0]), "=&v"(bfg[0][1]), "=&v"(bfg[0][2]), "=&v"(bfg[0][3]),
;             "=&v"(af[1][0]), "=&v"(af[1][1]), "=&v"(af[1][2]), "=&v"(af[1][3]), "=&v"(bfg[1][0]), "=&v"(bfg[1][1]), "=&v"(bfg[1][2]), "=&v"(bfg[1][3])
;           : "v"(arow + sw0 + bo), "v"(brw + sw0 + bo), "v"(arow + sw1 + bo), "v"(brw + sw1 + bo)
;           : "memory");
;     } else {
;       asm volatile(
;           "ds_read_b128 %0, %12\n\tds_read_b128 %1, %12 offset:2048\n\tds_read_b128 %2, %12 offset:4096\n\tds_read_b128 %3, %12 offset:6144\n\t"
;           "ds_read_b128 %4, %13\n\tds_read_b128 %5, %13 offset:2048\n\t"
;           "ds_read_b128 %6, %14\n\tds_read_b128 %7, %14 offset:2048\n\tds_read_b128 %8, %14 offset:4096\n\tds_read_b128 %9, %14 offset:6144\n\t"
	ds_read_b128 v[42:45], v9
	ds_read_b128 v[46:49], v9 offset:2048
	ds_read_b128 v[50:53], v9 offset:4096
	ds_read_b128 v[54:57], v9 offset:6144
	ds_read_b128 v[58:61], v10
	ds_read_b128 v[62:65], v10 offset:2048
	ds_read_b128 v[66:69], v11
	ds_read_b128 v[70:73], v11 offset:2048
	ds_read_b128 v[74:77], v11 offset:4096
	ds_read_b128 v[78:81], v11 offset:6144
	ds_read_b128 v[82:85], v12
	ds_read_b128 v[86:89], v12 offset:2048
	s_waitcnt lgkmcnt(0)
	s_setprio 1
	v_mfma_f32_16x16x32_bf16 v[4:7], v[42:45], v[58:61], v[4:7]
	v_mfma_f32_16x16x32_bf16 v[0:3], v[42:45], v[62:65], v[0:3]
	v_mfma_f32_16x16x32_bf16 v[8:11], v[46:49], v[58:61], v[34:37]
	v_mfma_f32_16x16x32_bf16 v[12:15], v[46:49], v[62:65], v[14:17]
	v_mfma_f32_16x16x32_bf16 v[34:37], v[50:53], v[58:61], v[38:41]
	v_mfma_f32_16x16x32_bf16 v[38:41], v[50:53], v[62:65], v[18:21]
	v_mfma_f32_16x16x32_bf16 v[42:45], v[54:57], v[58:61], v[26:29]
	v_mfma_f32_16x16x32_bf16 v[46:49], v[54:57], v[62:65], v[22:25]
	v_mfma_f32_16x16x32_bf16 v[28:31], v[66:69], v[82:85], v[4:7]
	v_mfma_f32_16x16x32_bf16 v[24:27], v[66:69], v[86:89], v[0:3]
	v_mfma_f32_16x16x32_bf16 v[20:23], v[70:73], v[82:85], v[8:11]
	v_mfma_f32_16x16x32_bf16 v[16:19], v[70:73], v[86:89], v[12:15]
	v_mfma_f32_16x16x32_bf16 v[12:15], v[74:77], v[82:85], v[34:37]
	v_mfma_f32_16x16x32_bf16 v[8:11], v[74:77], v[86:89], v[38:41]
	v_mfma_f32_16x16x32_bf16 v[0:3], v[78:81], v[82:85], v[42:45]
	v_mfma_f32_16x16x32_bf16 v[4:7], v[78:81], v[86:89], v[46:49]
	s_setprio 0
	s_ashr_i32 s3, s2, 1
	s_andn2_b32 s3, s3, 63
	s_lshl_b64 s[4:5], s[20:21], 2
	s_add_u32 s0, s0, s4
	s_addc_u32 s1, s1, s5
	s_lshl_b32 s2, s2, 1
	s_and_b32 s2, s2, 0x80
	v_lshrrev_b32_e32 v32, 2, v32
	s_add_u32 s0, s0, s2
	v_and_or_b32 v32, v32, 12, s18
	s_addc_u32 s1, s1, 0
	v_lshlrev_b32_e32 v128, 2, v33
	v_add_u32_e32 v32, s3, v32
	v_lshl_add_u64 v[34:35], s[0:1], 0, v[128:129]
	s_mov_b64 s[0:1], 0x2848400
	v_lshl_add_u64 v[34:35], v[34:35], 0, s[0:1]
	s_mov_b64 s[24:25], 0x1000
	s_mov_b64 s[26:27], 0x2000
	s_mov_b64 s[28:29], 0x3000
	v_mov_b32_e32 v128, v32
	v_cmp_gt_i32_e64 s[16:17], s79, v128
	v_lshlrev_b64 v[180:181], 12, v[128:129]
	v_lshl_add_u64 v[180:181], v[34:35], 0, v[180:181]
	v_lshl_add_u64 v[182:183], v[180:181], 0, s[24:25]
	v_lshl_add_u64 v[184:185], v[180:181], 0, s[26:27]
	v_lshl_add_u64 v[186:187], v[180:181], 0, s[28:29]
	v_or_b32_e32 v128, 16, v32
	v_cmp_gt_i32_e64 s[18:19], s79, v128
	v_lshlrev_b64 v[188:189], 12, v[128:129]
	v_lshl_add_u64 v[188:189], v[34:35], 0, v[188:189]
	v_lshl_add_u64 v[190:191], v[188:189], 0, s[24:25]
	v_lshl_add_u64 v[192:193], v[188:189], 0, s[26:27]
	v_lshl_add_u64 v[194:195], v[188:189], 0, s[28:29]
	v_or_b32_e32 v128, 32, v32
	v_cmp_gt_i32_e64 s[20:21], s79, v128
	v_lshlrev_b64 v[196:197], 12, v[128:129]
	v_lshl_add_u64 v[196:197], v[34:35], 0, v[196:197]
	v_lshl_add_u64 v[198:199], v[196:197], 0, s[24:25]
	v_lshl_add_u64 v[200:201], v[196:197], 0, s[26:27]
	v_lshl_add_u64 v[202:203], v[196:197], 0, s[28:29]
	v_or_b32_e32 v128, 48, v32
	v_cmp_gt_i32_e64 s[22:23], s79, v128
	v_lshlrev_b64 v[204:205], 12, v[128:129]
	v_lshl_add_u64 v[204:205], v[34:35], 0, v[204:205]
	v_lshl_add_u64 v[206:207], v[204:205], 0, s[24:25]
	v_lshl_add_u64 v[208:209], v[204:205], 0, s[26:27]
	v_lshl_add_u64 v[210:211], v[204:205], 0, s[28:29]
	s_mov_b64 exec, s[16:17]
	global_load_dword v68, v[180:181], off
	global_load_dword v69, v[180:181], off offset:64
	global_load_dword v70, v[182:183], off
	global_load_dword v71, v[182:183], off offset:64
	global_load_dword v72, v[184:185], off
	global_load_dword v73, v[184:185], off offset:64
	global_load_dword v74, v[186:187], off
	global_load_dword v75, v[186:187], off offset:64
	s_mov_b64 exec, s[18:19]
	global_load_dword v76, v[188:189], off
	global_load_dword v77, v[188:189], off offset:64
	global_load_dword v78, v[190:191], off
	global_load_dword v79, v[190:191], off offset:64
	global_load_dword v80, v[192:193], off
	global_load_dword v81, v[192:193], off offset:64
	global_load_dword v82, v[194:195], off
	global_load_dword v83, v[194:195], off offset:64
	s_mov_b64 exec, s[20:21]
	global_load_dword v84, v[196:197], off
	global_load_dword v85, v[196:197], off offset:64
	global_load_dword v86, v[198:199], off
	global_load_dword v87, v[198:199], off offset:64
	global_load_dword v88, v[200:201], off
	global_load_dword v89, v[200:201], off offset:64
	global_load_dword v90, v[202:203], off
	global_load_dword v91, v[202:203], off offset:64
	s_mov_b64 exec, s[22:23]
	global_load_dword v92, v[204:205], off
	global_load_dword v93, v[204:205], off offset:64
	global_load_dword v94, v[206:207], off
	global_load_dword v95, v[206:207], off offset:64
	global_load_dword v96, v[208:209], off
	global_load_dword v97, v[208:209], off offset:64
	global_load_dword v98, v[210:211], off
	global_load_dword v99, v[210:211], off offset:64
	s_mov_b64 exec, s[16:17]
	s_waitcnt vmcnt(31)
; template <int NF>
; DI void out_tile(const Params& p, int layer, int brow, int bcol, bool& first, bool hasNext, int nbrow, int nbcol) {
;     ...
; #pragma unroll
;   for (int m = 0; m < 4; ++m)
; #pragma unroll
;     for (int j = 0; j < 4; ++j) {
;       int row = brow + wr * 64 + m * 16 + fq * 4 + j;
;       if (row < ROWS) {
; #pragma unroll
;         for (int n = 0; n < NF; ++n) xres[(long)row * 1024 + bcol + wc * (NF * 16) + n * 16 + fr] += acc[m][n][j];
;       }
;     }
	v_add_f32_e32 v28, v28, v68
	global_store_dword v[180:181], v28, off
	s_waitcnt vmcnt(31)
	v_add_f32_e32 v24, v24, v69
	global_store_dword v[180:181], v24, off offset:64
	s_waitcnt vmcnt(31)
	v_add_f32_e32 v29, v29, v70
	global_store_dword v[182:183], v29, off
	s_waitcnt vmcnt(31)
	v_add_f32_e32 v25, v25, v71
	global_store_dword v[182:183], v25, off offset:64
	s_waitcnt vmcnt(31)
	v_add_f32_e32 v30, v30, v72
	global_store_dword v[184:185], v30, off
	s_waitcnt vmcnt(31)
	v_add_f32_e32 v26, v26, v73
	global_store_dword v[184:185], v26, off offset:64
	s_waitcnt vmcnt(31)
	v_add_f32_e32 v31, v31, v74
	global_store_dword v[186:187], v31, off
	s_waitcnt vmcnt(31)
	v_add_f32_e32 v27, v27, v75
	global_store_dword v[186:187], v27, off offset:64
	s_mov_b64 exec, s[18:19]
	s_waitcnt vmcnt(31)
	v_add_f32_e32 v20, v20, v76
	global_store_dword v[188:189], v20, off
	s_waitcnt vmcnt(31)
	v_add_f32_e32 v16, v16, v77
	global_store_dword v[188:189], v16, off offset:64
	s_waitcnt vmcnt(31)
	v_add_f32_e32 v21, v21, v78
	global_store_dword v[190:191], v21, off
	s_waitcnt vmcnt(31)
	v_add_f32_e32 v17, v17, v79
	global_store_dword v[190:191], v17, off offset:64
	s_waitcnt vmcnt(31)
	v_add_f32_e32 v22, v22, v80
	global_store_dword v[192:193], v22, off
	s_waitcnt vmcnt(31)
	v_add_f32_e32 v18, v18, v81
	global_store_dword v[192:193], v18, off offset:64
	s_waitcnt vmcnt(31)
	v_add_f32_e32 v23, v23, v82
	global_store_dword v[194:195], v23, off
	s_waitcnt vmcnt(31)
	v_add_f32_e32 v19, v19, v83
	global_store_dword v[194:195], v19, off offset:64
	s_mov_b64 exec, s[20:21]
	s_waitcnt vmcnt(31)
	v_add_f32_e32 v12, v12, v84
	global_store_dword v[196:197], v12, off
	s_waitcnt vmcnt(31)
	v_add_f32_e32 v8, v8, v85
	global_store_dword v[196:197], v8, off offset:64
	s_waitcnt vmcnt(31)
	v_add_f32_e32 v13, v13, v86
	global_store_dword v[198:199], v13, off
	s_waitcnt vmcnt(31)
	v_add_f32_e32 v9, v9, v87
	global_store_dword v[198:199], v9, off offset:64
	s_waitcnt vmcnt(31)
	v_add_f32_e32 v14, v14, v88
	global_store_dword v[200:201], v14, off
	s_waitcnt vmcnt(31)
	v_add_f32_e32 v10, v10, v89
	global_store_dword v[200:201], v10, off offset:64
	s_waitcnt vmcnt(31)
	v_add_f32_e32 v15, v15, v90
	global_store_dword v[202:203], v15, off
	s_waitcnt vmcnt(31)
	v_add_f32_e32 v11, v11, v91
	global_store_dword v[202:203], v11, off offset:64
	s_mov_b64 exec, s[22:23]
	s_waitcnt vmcnt(31)
	v_add_f32_e32 v0, v0, v92
	global_store_dword v[204:205], v0, off
	s_waitcnt vmcnt(31)
	v_add_f32_e32 v4, v4, v93
	global_store_dword v[204:205], v4, off offset:64
	s_waitcnt vmcnt(31)
	v_add_f32_e32 v1, v1, v94
	global_store_dword v[206:207], v1, off
	s_waitcnt vmcnt(31)
	v_add_f32_e32 v5, v5, v95
	global_store_dword v[206:207], v5, off offset:64
	s_waitcnt vmcnt(31)
	v_add_f32_e32 v2, v2, v96
	global_store_dword v[208:209], v2, off
	s_waitcnt vmcnt(31)
	v_add_f32_e32 v6, v6, v97
	global_store_dword v[208:209], v6, off offset:64
	s_waitcnt vmcnt(31)
	v_add_f32_e32 v3, v3, v98
	global_store_dword v[210:211], v3, off
	s_waitcnt vmcnt(31)
	v_add_f32_e32 v7, v7, v99
	global_store_dword v[210:211], v7, off offset:64
	s_mov_b64 exec, -1
	s_mov_b64 s[0:1], -1
